# v102 + K-loop head pointer selection (7 SALU) moved from load segment 1 (16 reads) to the start of segment 2 (8 reads)
# baseline (speedup 1.0000x reference)
; #define PG8_STAGE(bufoff, gbase, voff) do { _Pragma("unroll") for (int _i = 0; _i < 2; ++_i) \
;         __builtin_amdgcn_global_load_lds((const unsigned*)((const char*)(gbase) + (voff)[_i]), (PG8_LAS unsigned*)(lds + (bufoff) + ldsw + _i * 8192), 16, 0, 0); } while (0)
; #define PG8_LDA(dst, b, h) do { _Pragma("unroll") for (int m = 0; m < 4; ++m) _Pragma("unroll") for (int k = 0; k < 2; ++k) dst[m][k] = *(const PG8_LAS bf16x8*)(lds + PG8_SA(b, h) + aoff + m * 2048 + k * 1024); } while (0)
; #define PG8_LDB(dst, b, h) do { _Pragma("unroll") for (int n = 0; n < 2; ++n) _Pragma("unroll") for (int k = 0; k < 2; ++k) dst[n][k] = *(const PG8_LAS bf16x8*)(lds + PG8_SB(b, h) + boff + n * 2048 + k * 1024); } while (0)
; #define PG8_WAIT_V(n) asm volatile("s_waitcnt vmcnt(" #n ")" ::: "memory")
; #define PG8_WAIT_L(n) asm volatile("s_waitcnt lgkmcnt(" #n ")" ::: "memory")
; #define PG8_BAR __builtin_amdgcn_s_barrier()
; #define PG8_SCHED __builtin_amdgcn_sched_barrier(0)
; template <class Epi, class Sched, bool ALIGN_EPI = false, bool SP2 = false>
; __device__ __forceinline__ void gemm_phase(PG8_LAS unsigned char* lds, const Gemm g, const Sched& S, const Epi& E) {
;     ...
;         const bool has_next = S.next(ui + 1, nxt);
;         const char* nA = has_next ? (const char*)g.A + (size_t)nxt.pm * tstep : cA; const char* nB = has_next ? (const char*)g.Bt + (size_t)nxt.pn * tstep : cB;
;         for (int t = 0; t < nt; t += 2) {
;             const bool last = (t == nt - 2);
;             const char* a1 = cA + (size_t)(t + 1) * kstep;
;             const char* a2 = last ? nA : cA + (size_t)(t + 2) * kstep; const char* b2 = last ? nB : cB + (size_t)(t + 2) * kstep;
;             const char* a3 = a2 + kstep; const char* b3 = b2 + kstep;
;             if (last && has_next) S.a_ready(nxt);
;             if constexpr (SP2) {
;             PG8_LDB(B0, 0, 0); PG8_LDB(B1, 0, 1); PG8_SCHED; PG8_LDA(At, 0, 0); PG8_STAGE(PG8_SA(1, 1), a1 + hstep, voffA);
;             PG8_WAIT_V(8); PG8_WAIT_L(0); PG8_BAR; PG8_MMA(0, 0, At, B0); PG8_MMA(0, 1, At, B1); PG8_BAR; PG8_SCHED;
;             PG8_LDA(At, 0, 1); PG8_STAGE(PG8_SB(0, 0), b2, voffB); PG8_STAGE(PG8_SB(0, 1), b2 + hstep, voffB); PG8_STAGE(PG8_SA(0, 0), a2, voffA);
;             PG8_WAIT_V(8); PG8_WAIT_L(0); PG8_BAR; PG8_MMA(1, 0, At, B0); PG8_MMA(1, 1, At, B1); PG8_BAR; PG8_SCHED;
.LBB0_99:
	s_ashr_i32 s21, s20, 31
	s_lshl_b64 s[24:25], s[20:21], 19
	s_add_u32 s24, s35, s24
	s_addc_u32 s25, s38, s25
	s_and_b64 s[26:27], s[4:5], exec
	s_cselect_b32 s3, s25, s9
	s_cselect_b32 s7, s24, s8
	s_ashr_i32 s23, s22, 31
	s_lshl_b64 s[26:27], s[22:23], 19
	s_add_u32 s26, s39, s26
	s_addc_u32 s27, s40, s27
	s_and_b64 s[30:31], s[4:5], exec
	s_cselect_b32 s11, s27, s29
	s_cselect_b32 s21, s26, s28
	s_add_u32 s8, s8, 0x40080
	s_addc_u32 s9, s9, 0
	s_add_u32 s23, s28, 0x100
	s_addc_u32 s44, s29, 0
	s_mov_b32 s45, -2
	ds_read_b128 v[132:135], v204
	ds_read_b128 v[136:139], v204 offset:1024
	ds_read_b128 v[140:143], v204 offset:2048
	ds_read_b128 v[144:147], v204 offset:3072
	ds_read_b128 v[148:151], v204 offset:16384
	ds_read_b128 v[152:155], v204 offset:17408
	ds_read_b128 v[156:159], v204 offset:18432
	ds_read_b128 v[160:163], v204 offset:19456
	v_lshl_add_u64 v[194:195], s[8:9], 0, v[178:179]
	s_add_i32 m0, s42, 0xc000
	ds_read_b128 v[164:167], v205
	ds_read_b128 v[182:185], v205 offset:1024
	ds_read_b128 v[186:189], v205 offset:2048
	ds_read_b128 v[190:193], v205 offset:3072
	ds_read_b128 v[208:211], v205 offset:4096
	ds_read_b128 v[212:215], v205 offset:5120
	ds_read_b128 v[216:219], v205 offset:6144
	ds_read_b128 v[220:223], v205 offset:7168
	global_load_lds_dwordx4 v[194:195], off
	s_add_i32 m0, s42, 0xe000
	v_lshl_add_u64 v[194:195], s[8:9], 0, v[180:181]
	global_load_lds_dwordx4 v[194:195], off
	s_waitcnt vmcnt(8) lgkmcnt(0)
	s_barrier
	s_setprio 1
	v_mfma_f32_16x16x32_bf16 v[128:131], v[132:135], v[164:167], 0
	v_mfma_f32_16x16x32_bf16 v[124:127], v[140:143], v[164:167], 0
	v_mfma_f32_16x16x32_bf16 v[112:115], v[132:135], v[186:189], 0
	v_mfma_f32_16x16x32_bf16 v[108:111], v[140:143], v[186:189], 0
	v_mfma_f32_16x16x32_bf16 v[96:99], v[132:135], v[208:211], 0
	v_mfma_f32_16x16x32_bf16 v[92:95], v[140:143], v[208:211], 0
	v_mfma_f32_16x16x32_bf16 v[80:83], v[132:135], v[216:219], 0
	v_mfma_f32_16x16x32_bf16 v[76:79], v[140:143], v[216:219], 0
	v_mfma_f32_16x16x32_bf16 v[128:131], v[136:139], v[182:185], v[128:131]
	v_mfma_f32_16x16x32_bf16 v[124:127], v[144:147], v[182:185], v[124:127]
	v_mfma_f32_16x16x32_bf16 v[112:115], v[136:139], v[190:193], v[112:115]
	v_mfma_f32_16x16x32_bf16 v[108:111], v[144:147], v[190:193], v[108:111]
	v_mfma_f32_16x16x32_bf16 v[96:99], v[136:139], v[212:215], v[96:99]
	v_mfma_f32_16x16x32_bf16 v[92:95], v[144:147], v[212:215], v[92:95]
	v_mfma_f32_16x16x32_bf16 v[80:83], v[136:139], v[220:223], v[80:83]
	v_mfma_f32_16x16x32_bf16 v[76:79], v[144:147], v[220:223], v[76:79]
	s_setprio 0
	s_setprio 1
	v_mfma_f32_16x16x32_bf16 v[120:123], v[148:151], v[164:167], 0
	v_mfma_f32_16x16x32_bf16 v[116:119], v[156:159], v[164:167], 0
	v_mfma_f32_16x16x32_bf16 v[104:107], v[148:151], v[186:189], 0
	v_mfma_f32_16x16x32_bf16 v[100:103], v[156:159], v[186:189], 0
	v_mfma_f32_16x16x32_bf16 v[88:91], v[148:151], v[208:211], 0
	v_mfma_f32_16x16x32_bf16 v[84:87], v[156:159], v[208:211], 0
	v_mfma_f32_16x16x32_bf16 v[72:75], v[148:151], v[216:219], 0
	v_mfma_f32_16x16x32_bf16 v[68:71], v[156:159], v[216:219], 0
	v_mfma_f32_16x16x32_bf16 v[120:123], v[152:155], v[182:185], v[120:123]
	v_mfma_f32_16x16x32_bf16 v[116:119], v[160:163], v[182:185], v[116:119]
	v_mfma_f32_16x16x32_bf16 v[104:107], v[152:155], v[190:193], v[104:107]
	v_mfma_f32_16x16x32_bf16 v[100:103], v[160:163], v[190:193], v[100:103]
	v_mfma_f32_16x16x32_bf16 v[88:91], v[152:155], v[212:215], v[88:91]
	v_mfma_f32_16x16x32_bf16 v[84:87], v[160:163], v[212:215], v[84:87]
	v_mfma_f32_16x16x32_bf16 v[72:75], v[152:155], v[220:223], v[72:75]
	v_mfma_f32_16x16x32_bf16 v[68:71], v[160:163], v[220:223], v[68:71]
	s_setprio 0
	s_barrier
	s_add_u32 s28, s8, 0xfffc0080
	s_addc_u32 s29, s9, -1
	s_cmp_eq_u32 s45, 12
	s_cselect_b32 s31, s3, s29
	s_cselect_b32 s30, s7, s28
	s_cselect_b32 s29, s11, s44
	s_cselect_b32 s28, s21, s23
	v_lshl_add_u64 v[194:195], s[28:29], 0, v[168:169]
	s_add_i32 m0, s41, 0x10000
	ds_read_b128 v[164:167], v205 offset:16384
	ds_read_b128 v[182:185], v205 offset:17408
	ds_read_b128 v[186:189], v205 offset:18432
	ds_read_b128 v[190:193], v205 offset:19456
	ds_read_b128 v[208:211], v205 offset:20480
	ds_read_b128 v[212:215], v205 offset:21504
	ds_read_b128 v[216:219], v205 offset:22528
	ds_read_b128 v[220:223], v205 offset:23552
	global_load_lds_dwordx4 v[194:195], off
	s_add_i32 m0, s41, 0x12000
	s_add_u32 s54, s28, 0x40000
	v_lshl_add_u64 v[202:203], s[28:29], 0, v[172:173]
	s_addc_u32 s55, s29, 0
	global_load_lds_dwordx4 v[202:203], off
	v_lshl_add_u64 v[224:225], s[54:55], 0, v[168:169]
	s_add_i32 m0, s41, 0x14000
	v_lshl_add_u64 v[226:227], s[30:31], 0, v[170:171]
	global_load_lds_dwordx4 v[224:225], off
	s_add_i32 m0, s41, 0x16000
	v_lshl_add_u64 v[224:225], s[54:55], 0, v[172:173]
	global_load_lds_dwordx4 v[224:225], off
	v_lshl_add_u64 v[224:225], s[30:31], 0, v[0:1]
	s_waitcnt vmcnt(6) lgkmcnt(0)
	s_barrier
; #define PG8_MMA(ai, bj, At, Bt) do { __builtin_amdgcn_s_setprio(1); _Pragma("unroll") for (int m = 0; m < 4; ++m) _Pragma("unroll") for (int n = 0; n < 2; ++n) _Pragma("unroll") for (int k = 0; k < 2; ++k) \
;         acc[ai][bj][m][n] = __builtin_amdgcn_mfma_f32_16x16x32_bf16(Bt[n][k], At[m][k], acc[ai][bj][m][n], 0, 0, 0); __builtin_amdgcn_s_setprio(0); } while (0)
; #define PG8_WAIT_V(n) asm volatile("s_waitcnt vmcnt(" #n ")" ::: "memory")
; #define PG8_WAIT_L(n) asm volatile("s_waitcnt lgkmcnt(" #n ")" ::: "memory")
; #define PG8_BAR __builtin_amdgcn_s_barrier()
; #define PG8_SCHED __builtin_amdgcn_sched_barrier(0)
; template <class Epi, class Sched, bool ALIGN_EPI = false, bool SP2 = false>
; __device__ __forceinline__ void gemm_phase(PG8_LAS unsigned char* lds, const Gemm g, const Sched& S, const Epi& E) {
;     ...
;             PG8_WAIT_V(8); PG8_WAIT_L(0); PG8_BAR; PG8_MMA(1, 0, At, B0); PG8_MMA(1, 1, At, B1); PG8_BAR; PG8_SCHED;
	s_setprio 1
	v_mfma_f32_16x16x32_bf16 v[64:67], v[132:135], v[164:167], 0
	v_mfma_f32_16x16x32_bf16 v[60:63], v[140:143], v[164:167], 0
	v_mfma_f32_16x16x32_bf16 v[48:51], v[132:135], v[186:189], 0
	v_mfma_f32_16x16x32_bf16 v[44:47], v[140:143], v[186:189], 0
	v_mfma_f32_16x16x32_bf16 v[32:35], v[132:135], v[208:211], 0
	v_mfma_f32_16x16x32_bf16 v[28:31], v[140:143], v[208:211], 0
	v_mfma_f32_16x16x32_bf16 v[16:19], v[132:135], v[216:219], 0
	v_mfma_f32_16x16x32_bf16 v[12:15], v[140:143], v[216:219], 0
	v_mfma_f32_16x16x32_bf16 v[64:67], v[136:139], v[182:185], v[64:67]
	v_mfma_f32_16x16x32_bf16 v[60:63], v[144:147], v[182:185], v[60:63]
	v_mfma_f32_16x16x32_bf16 v[48:51], v[136:139], v[190:193], v[48:51]
	v_mfma_f32_16x16x32_bf16 v[44:47], v[144:147], v[190:193], v[44:47]
	v_mfma_f32_16x16x32_bf16 v[32:35], v[136:139], v[212:215], v[32:35]
	v_mfma_f32_16x16x32_bf16 v[28:31], v[144:147], v[212:215], v[28:31]
	v_mfma_f32_16x16x32_bf16 v[16:19], v[136:139], v[220:223], v[16:19]
	v_mfma_f32_16x16x32_bf16 v[12:15], v[144:147], v[220:223], v[12:15]
	s_setprio 0
	s_setprio 1
	v_mfma_f32_16x16x32_bf16 v[56:59], v[148:151], v[164:167], 0
	v_mfma_f32_16x16x32_bf16 v[52:55], v[156:159], v[164:167], 0
	v_mfma_f32_16x16x32_bf16 v[40:43], v[148:151], v[186:189], 0
	v_mfma_f32_16x16x32_bf16 v[36:39], v[156:159], v[186:189], 0
	v_mfma_f32_16x16x32_bf16 v[24:27], v[148:151], v[208:211], 0
	v_mfma_f32_16x16x32_bf16 v[20:23], v[156:159], v[208:211], 0
	v_mfma_f32_16x16x32_bf16 v[8:11], v[148:151], v[216:219], 0
	v_mfma_f32_16x16x32_bf16 v[4:7], v[156:159], v[216:219], 0
	v_mfma_f32_16x16x32_bf16 v[56:59], v[152:155], v[182:185], v[56:59]
	v_mfma_f32_16x16x32_bf16 v[52:55], v[160:163], v[182:185], v[52:55]
	v_mfma_f32_16x16x32_bf16 v[40:43], v[152:155], v[190:193], v[40:43]
	v_mfma_f32_16x16x32_bf16 v[36:39], v[160:163], v[190:193], v[36:39]
	v_mfma_f32_16x16x32_bf16 v[24:27], v[152:155], v[212:215], v[24:27]
	v_mfma_f32_16x16x32_bf16 v[20:23], v[160:163], v[212:215], v[20:23]
	v_mfma_f32_16x16x32_bf16 v[8:11], v[152:155], v[220:223], v[8:11]
	v_mfma_f32_16x16x32_bf16 v[4:7], v[160:163], v[220:223], v[4:7]
	s_setprio 0
	s_barrier
	s_branch .Lkmid_0
; #define PG8_STAGE(bufoff, gbase, voff) do { _Pragma("unroll") for (int _i = 0; _i < 2; ++_i) \
;         __builtin_amdgcn_global_load_lds((const unsigned*)((const char*)(gbase) + (voff)[_i]), (PG8_LAS unsigned*)(lds + (bufoff) + ldsw + _i * 8192), 16, 0, 0); } while (0)
; #define PG8_LDA(dst, b, h) do { _Pragma("unroll") for (int m = 0; m < 4; ++m) _Pragma("unroll") for (int k = 0; k < 2; ++k) dst[m][k] = *(const PG8_LAS bf16x8*)(lds + PG8_SA(b, h) + aoff + m * 2048 + k * 1024); } while (0)
; #define PG8_LDB(dst, b, h) do { _Pragma("unroll") for (int n = 0; n < 2; ++n) _Pragma("unroll") for (int k = 0; k < 2; ++k) dst[n][k] = *(const PG8_LAS bf16x8*)(lds + PG8_SB(b, h) + boff + n * 2048 + k * 1024); } while (0)
; #define PG8_MMA(ai, bj, At, Bt) do { __builtin_amdgcn_s_setprio(1); _Pragma("unroll") for (int m = 0; m < 4; ++m) _Pragma("unroll") for (int n = 0; n < 2; ++n) _Pragma("unroll") for (int k = 0; k < 2; ++k) \
;         acc[ai][bj][m][n] = __builtin_amdgcn_mfma_f32_16x16x32_bf16(Bt[n][k], At[m][k], acc[ai][bj][m][n], 0, 0, 0); __builtin_amdgcn_s_setprio(0); } while (0)
; #define PG8_WAIT_V(n) asm volatile("s_waitcnt vmcnt(" #n ")" ::: "memory")
; #define PG8_WAIT_L(n) asm volatile("s_waitcnt lgkmcnt(" #n ")" ::: "memory")
; template <class Epi, class Sched, bool ALIGN_EPI = false, bool SP2 = false>
; __device__ __forceinline__ void gemm_phase(PG8_LAS unsigned char* lds, const Gemm g, const Sched& S, const Epi& E) {
;     ...
;             const bool last = (t == nt - 2);
;             const char* a1 = cA + (size_t)(t + 1) * kstep;
;             const char* a2 = last ? nA : cA + (size_t)(t + 2) * kstep; const char* b2 = last ? nB : cB + (size_t)(t + 2) * kstep;
;             const char* a3 = a2 + kstep; const char* b3 = b2 + kstep;
;             if (last && has_next) S.a_ready(nxt);
;             if constexpr (SP2) {
;             PG8_LDB(B0, 0, 0); PG8_LDB(B1, 0, 1); PG8_SCHED; PG8_LDA(At, 0, 0); PG8_STAGE(PG8_SA(1, 1), a1 + hstep, voffA);
;             PG8_WAIT_V(8); PG8_WAIT_L(0); PG8_BAR; PG8_MMA(0, 0, At, B0); PG8_MMA(0, 1, At, B1); PG8_BAR; PG8_SCHED;
;             PG8_LDA(At, 0, 1); PG8_STAGE(PG8_SB(0, 0), b2, voffB); PG8_STAGE(PG8_SB(0, 1), b2 + hstep, voffB); PG8_STAGE(PG8_SA(0, 0), a2, voffA);
;             PG8_WAIT_V(8); PG8_WAIT_L(0); PG8_BAR; PG8_MMA(1, 0, At, B0); PG8_MMA(1, 1, At, B1); PG8_BAR; PG8_SCHED;
.LBB0_100:
	s_add_i32 m0, s50, 0xffffff80
	ds_read_b128 v[132:135], v204
	ds_read_b128 v[136:139], v204 offset:1024
	ds_read_b128 v[140:143], v204 offset:2048
	ds_read_b128 v[144:147], v204 offset:3072
	ds_read_b128 v[148:151], v204 offset:16384
	ds_read_b128 v[152:155], v204 offset:17408
	ds_read_b128 v[156:159], v204 offset:18432
	ds_read_b128 v[160:163], v204 offset:19456
	global_load_lds_dwordx4 v[224:225], off offset:128
	s_add_i32 m0, s51, 0xffffff80
	v_lshl_add_u64 v[194:195], s[8:9], 0, v[178:179]
	global_load_lds_dwordx4 v[226:227], off offset:128
	s_add_i32 m0, s42, 0xc000
	ds_read_b128 v[164:167], v205
	ds_read_b128 v[182:185], v205 offset:1024
	ds_read_b128 v[186:189], v205 offset:2048
	ds_read_b128 v[190:193], v205 offset:3072
	ds_read_b128 v[208:211], v205 offset:4096
	ds_read_b128 v[212:215], v205 offset:5120
	ds_read_b128 v[216:219], v205 offset:6144
	ds_read_b128 v[220:223], v205 offset:7168
	global_load_lds_dwordx4 v[194:195], off
	s_add_i32 m0, s42, 0xe000
	v_lshl_add_u64 v[194:195], s[8:9], 0, v[180:181]
	global_load_lds_dwordx4 v[194:195], off
	s_waitcnt vmcnt(8) lgkmcnt(0)
	s_barrier
	s_setprio 1
	v_mfma_f32_16x16x32_bf16 v[128:131], v[132:135], v[164:167], v[128:131]
	v_mfma_f32_16x16x32_bf16 v[124:127], v[140:143], v[164:167], v[124:127]
	v_mfma_f32_16x16x32_bf16 v[112:115], v[132:135], v[186:189], v[112:115]
	v_mfma_f32_16x16x32_bf16 v[108:111], v[140:143], v[186:189], v[108:111]
	v_mfma_f32_16x16x32_bf16 v[96:99], v[132:135], v[208:211], v[96:99]
	v_mfma_f32_16x16x32_bf16 v[92:95], v[140:143], v[208:211], v[92:95]
	v_mfma_f32_16x16x32_bf16 v[80:83], v[132:135], v[216:219], v[80:83]
	v_mfma_f32_16x16x32_bf16 v[76:79], v[140:143], v[216:219], v[76:79]
	v_mfma_f32_16x16x32_bf16 v[128:131], v[136:139], v[182:185], v[128:131]
	v_mfma_f32_16x16x32_bf16 v[124:127], v[144:147], v[182:185], v[124:127]
	v_mfma_f32_16x16x32_bf16 v[112:115], v[136:139], v[190:193], v[112:115]
	v_mfma_f32_16x16x32_bf16 v[108:111], v[144:147], v[190:193], v[108:111]
	v_mfma_f32_16x16x32_bf16 v[96:99], v[136:139], v[212:215], v[96:99]
	v_mfma_f32_16x16x32_bf16 v[92:95], v[144:147], v[212:215], v[92:95]
	v_mfma_f32_16x16x32_bf16 v[80:83], v[136:139], v[220:223], v[80:83]
	v_mfma_f32_16x16x32_bf16 v[76:79], v[144:147], v[220:223], v[76:79]
	s_setprio 0
	s_setprio 1
	v_mfma_f32_16x16x32_bf16 v[120:123], v[148:151], v[164:167], v[120:123]
	v_mfma_f32_16x16x32_bf16 v[116:119], v[156:159], v[164:167], v[116:119]
	v_mfma_f32_16x16x32_bf16 v[104:107], v[148:151], v[186:189], v[104:107]
	v_mfma_f32_16x16x32_bf16 v[100:103], v[156:159], v[186:189], v[100:103]
	v_mfma_f32_16x16x32_bf16 v[88:91], v[148:151], v[208:211], v[88:91]
	v_mfma_f32_16x16x32_bf16 v[84:87], v[156:159], v[208:211], v[84:87]
	v_mfma_f32_16x16x32_bf16 v[72:75], v[148:151], v[216:219], v[72:75]
	v_mfma_f32_16x16x32_bf16 v[68:71], v[156:159], v[216:219], v[68:71]
	v_mfma_f32_16x16x32_bf16 v[120:123], v[152:155], v[182:185], v[120:123]
	v_mfma_f32_16x16x32_bf16 v[116:119], v[160:163], v[182:185], v[116:119]
	v_mfma_f32_16x16x32_bf16 v[104:107], v[152:155], v[190:193], v[104:107]
	v_mfma_f32_16x16x32_bf16 v[100:103], v[160:163], v[190:193], v[100:103]
	v_mfma_f32_16x16x32_bf16 v[88:91], v[152:155], v[212:215], v[88:91]
	v_mfma_f32_16x16x32_bf16 v[84:87], v[160:163], v[212:215], v[84:87]
	v_mfma_f32_16x16x32_bf16 v[72:75], v[152:155], v[220:223], v[72:75]
	v_mfma_f32_16x16x32_bf16 v[68:71], v[160:163], v[220:223], v[68:71]
	s_setprio 0
	s_barrier
	s_add_u32 s28, s8, 0xfffc0080
	s_addc_u32 s29, s9, -1
	s_cmp_eq_u32 s45, 12
	s_cselect_b32 s31, s3, s29
	s_cselect_b32 s30, s7, s28
	s_cselect_b32 s29, s11, s44
	s_cselect_b32 s28, s21, s23
	v_lshl_add_u64 v[194:195], s[28:29], 0, v[168:169]
	s_add_i32 m0, s41, 0x10000
	ds_read_b128 v[164:167], v205 offset:16384
	ds_read_b128 v[182:185], v205 offset:17408
	ds_read_b128 v[186:189], v205 offset:18432
	ds_read_b128 v[190:193], v205 offset:19456
	ds_read_b128 v[208:211], v205 offset:20480
	ds_read_b128 v[212:215], v205 offset:21504
	ds_read_b128 v[216:219], v205 offset:22528
	ds_read_b128 v[220:223], v205 offset:23552
	global_load_lds_dwordx4 v[194:195], off
	s_add_i32 m0, s41, 0x12000
	s_add_u32 s54, s28, 0x40000
	v_lshl_add_u64 v[202:203], s[28:29], 0, v[172:173]
	s_addc_u32 s55, s29, 0
	global_load_lds_dwordx4 v[202:203], off
	v_lshl_add_u64 v[224:225], s[54:55], 0, v[168:169]
	s_add_i32 m0, s41, 0x14000
	v_lshl_add_u64 v[226:227], s[30:31], 0, v[170:171]
	global_load_lds_dwordx4 v[224:225], off
	s_add_i32 m0, s41, 0x16000
	v_lshl_add_u64 v[224:225], s[54:55], 0, v[172:173]
	global_load_lds_dwordx4 v[224:225], off
	v_lshl_add_u64 v[224:225], s[30:31], 0, v[0:1]
	s_waitcnt vmcnt(6) lgkmcnt(0)
	s_barrier
	s_setprio 1
	v_mfma_f32_16x16x32_bf16 v[64:67], v[132:135], v[164:167], v[64:67]
	v_mfma_f32_16x16x32_bf16 v[60:63], v[140:143], v[164:167], v[60:63]
	v_mfma_f32_16x16x32_bf16 v[48:51], v[132:135], v[186:189], v[48:51]
	v_mfma_f32_16x16x32_bf16 v[44:47], v[140:143], v[186:189], v[44:47]
	v_mfma_f32_16x16x32_bf16 v[32:35], v[132:135], v[208:211], v[32:35]
	v_mfma_f32_16x16x32_bf16 v[28:31], v[140:143], v[208:211], v[28:31]
	v_mfma_f32_16x16x32_bf16 v[16:19], v[132:135], v[216:219], v[16:19]
	v_mfma_f32_16x16x32_bf16 v[12:15], v[140:143], v[216:219], v[12:15]
	v_mfma_f32_16x16x32_bf16 v[64:67], v[136:139], v[182:185], v[64:67]
	v_mfma_f32_16x16x32_bf16 v[60:63], v[144:147], v[182:185], v[60:63]
	v_mfma_f32_16x16x32_bf16 v[48:51], v[136:139], v[190:193], v[48:51]
	v_mfma_f32_16x16x32_bf16 v[44:47], v[144:147], v[190:193], v[44:47]
	v_mfma_f32_16x16x32_bf16 v[32:35], v[136:139], v[212:215], v[32:35]
	v_mfma_f32_16x16x32_bf16 v[28:31], v[144:147], v[212:215], v[28:31]
	v_mfma_f32_16x16x32_bf16 v[16:19], v[136:139], v[220:223], v[16:19]
	v_mfma_f32_16x16x32_bf16 v[12:15], v[144:147], v[220:223], v[12:15]
	s_setprio 0
	s_setprio 1
	v_mfma_f32_16x16x32_bf16 v[56:59], v[148:151], v[164:167], v[56:59]
	v_mfma_f32_16x16x32_bf16 v[52:55], v[156:159], v[164:167], v[52:55]
	v_mfma_f32_16x16x32_bf16 v[40:43], v[148:151], v[186:189], v[40:43]
	v_mfma_f32_16x16x32_bf16 v[36:39], v[156:159], v[186:189], v[36:39]
	v_mfma_f32_16x16x32_bf16 v[24:27], v[148:151], v[208:211], v[24:27]
	v_mfma_f32_16x16x32_bf16 v[20:23], v[156:159], v[208:211], v[20:23]
	v_mfma_f32_16x16x32_bf16 v[8:11], v[148:151], v[216:219], v[8:11]
	v_mfma_f32_16x16x32_bf16 v[4:7], v[156:159], v[216:219], v[4:7]
	v_mfma_f32_16x16x32_bf16 v[56:59], v[152:155], v[182:185], v[56:59]
	v_mfma_f32_16x16x32_bf16 v[52:55], v[160:163], v[182:185], v[52:55]
	v_mfma_f32_16x16x32_bf16 v[40:43], v[152:155], v[190:193], v[40:43]
	v_mfma_f32_16x16x32_bf16 v[36:39], v[160:163], v[190:193], v[36:39]
	v_mfma_f32_16x16x32_bf16 v[24:27], v[152:155], v[212:215], v[24:27]
	v_mfma_f32_16x16x32_bf16 v[20:23], v[160:163], v[212:215], v[20:23]
	v_mfma_f32_16x16x32_bf16 v[8:11], v[152:155], v[220:223], v[8:11]
	v_mfma_f32_16x16x32_bf16 v[4:7], v[160:163], v[220:223], v[4:7]
	s_setprio 0
	s_barrier

; #define PG8_STAGE(bufoff, gbase, voff) do { _Pragma("unroll") for (int _i = 0; _i < 2; ++_i) \
;         __builtin_amdgcn_global_load_lds((const unsigned*)((const char*)(gbase) + (voff)[_i]), (PG8_LAS unsigned*)(lds + (bufoff) + ldsw + _i * 8192), 16, 0, 0); } while (0)
; #define PG8_LDA(dst, b, h) do { _Pragma("unroll") for (int m = 0; m < 4; ++m) _Pragma("unroll") for (int k = 0; k < 2; ++k) dst[m][k] = *(const PG8_LAS bf16x8*)(lds + PG8_SA(b, h) + aoff + m * 2048 + k * 1024); } while (0)
; #define PG8_LDB(dst, b, h) do { _Pragma("unroll") for (int n = 0; n < 2; ++n) _Pragma("unroll") for (int k = 0; k < 2; ++k) dst[n][k] = *(const PG8_LAS bf16x8*)(lds + PG8_SB(b, h) + boff + n * 2048 + k * 1024); } while (0)
; #define PG8_WAIT_V(n) asm volatile("s_waitcnt vmcnt(" #n ")" ::: "memory")
; #define PG8_WAIT_L(n) asm volatile("s_waitcnt lgkmcnt(" #n ")" ::: "memory")
; #define PG8_BAR __builtin_amdgcn_s_barrier()
; #define PG8_SCHED __builtin_amdgcn_sched_barrier(0)
; template <class Epi, class Sched, bool ALIGN_EPI = false, bool SP2 = false>
; __device__ __forceinline__ void gemm_phase(PG8_LAS unsigned char* lds, const Gemm g, const Sched& S, const Epi& E) {
;     ...
;         const bool has_next = S.next(ui + 1, nxt);
;         const char* nA = has_next ? (const char*)g.A + (size_t)nxt.pm * tstep : cA; const char* nB = has_next ? (const char*)g.Bt + (size_t)nxt.pn * tstep : cB;
;         for (int t = 0; t < nt; t += 2) {
;             const bool last = (t == nt - 2);
;             const char* a1 = cA + (size_t)(t + 1) * kstep;
;             const char* a2 = last ? nA : cA + (size_t)(t + 2) * kstep; const char* b2 = last ? nB : cB + (size_t)(t + 2) * kstep;
;             const char* a3 = a2 + kstep; const char* b3 = b2 + kstep;
;             if (last && has_next) S.a_ready(nxt);
;             if constexpr (SP2) {
;             PG8_LDB(B0, 0, 0); PG8_LDB(B1, 0, 1); PG8_SCHED; PG8_LDA(At, 0, 0); PG8_STAGE(PG8_SA(1, 1), a1 + hstep, voffA);
;             PG8_WAIT_V(8); PG8_WAIT_L(0); PG8_BAR; PG8_MMA(0, 0, At, B0); PG8_MMA(0, 1, At, B1); PG8_BAR; PG8_SCHED;
;             PG8_LDA(At, 0, 1); PG8_STAGE(PG8_SB(0, 0), b2, voffB); PG8_STAGE(PG8_SB(0, 1), b2 + hstep, voffB); PG8_STAGE(PG8_SA(0, 0), a2, voffA);
;             PG8_WAIT_V(8); PG8_WAIT_L(0); PG8_BAR; PG8_MMA(1, 0, At, B0); PG8_MMA(1, 1, At, B1); PG8_BAR; PG8_SCHED;
.LBB0_328:
	s_ashr_i32 s17, s16, 31
	s_lshl_b64 s[20:21], s[16:17], 19
	s_add_u32 s20, s37, s20
	s_addc_u32 s21, s38, s21
	s_and_b64 s[22:23], s[6:7], exec
	s_cselect_b32 s3, s21, s29
	s_cselect_b32 s17, s20, s28
	s_ashr_i32 s19, s18, 31
	s_lshl_b64 s[22:23], s[18:19], 19
	s_add_u32 s22, s39, s22
	s_addc_u32 s23, s40, s23
	s_and_b64 s[34:35], s[6:7], exec
	s_cselect_b32 s19, s23, s31
	s_cselect_b32 s25, s22, s30
	s_add_u32 s28, s28, 0x40080
	s_addc_u32 s29, s29, 0
	s_add_u32 s27, s30, 0x100
	s_addc_u32 s44, s31, 0
	s_mov_b32 s45, -2
	ds_read_b128 v[108:111], v251
	ds_read_b128 v[112:115], v251 offset:1024
	ds_read_b128 v[124:127], v251 offset:2048
	ds_read_b128 v[128:131], v251 offset:3072
	ds_read_b128 v[132:135], v251 offset:16384
	ds_read_b128 v[140:143], v251 offset:17408
	ds_read_b128 v[148:151], v251 offset:18432
	ds_read_b128 v[156:159], v251 offset:19456
	v_lshl_add_u64 v[212:213], s[28:29], 0, v[208:209]
	s_add_i32 m0, s42, 0xc000
	ds_read_b128 v[164:167], v253
	ds_read_b128 v[168:171], v253 offset:1024
	ds_read_b128 v[172:175], v253 offset:2048
	ds_read_b128 v[176:179], v253 offset:3072
	ds_read_b128 v[180:183], v253 offset:4096
	ds_read_b128 v[184:187], v253 offset:5120
	ds_read_b128 v[188:191], v253 offset:6144
	ds_read_b128 v[192:195], v253 offset:7168
	global_load_lds_dwordx4 v[212:213], off
	s_add_i32 m0, s42, 0xe000
	v_lshl_add_u64 v[212:213], s[28:29], 0, v[210:211]
	global_load_lds_dwordx4 v[212:213], off
	s_waitcnt vmcnt(8) lgkmcnt(0)
	s_barrier
	s_setprio 1
	v_mfma_f32_16x16x32_bf16 v[160:163], v[108:111], v[164:167], 0
	v_mfma_f32_16x16x32_bf16 v[152:155], v[124:127], v[164:167], 0
	v_mfma_f32_16x16x32_bf16 v[120:123], v[108:111], v[172:175], 0
	v_mfma_f32_16x16x32_bf16 v[116:119], v[124:127], v[172:175], 0
	v_mfma_f32_16x16x32_bf16 v[96:99], v[108:111], v[180:183], 0
	v_mfma_f32_16x16x32_bf16 v[92:95], v[124:127], v[180:183], 0
	v_mfma_f32_16x16x32_bf16 v[80:83], v[108:111], v[188:191], 0
	v_mfma_f32_16x16x32_bf16 v[76:79], v[124:127], v[188:191], 0
	v_mfma_f32_16x16x32_bf16 v[160:163], v[112:115], v[168:171], v[160:163]
	v_mfma_f32_16x16x32_bf16 v[152:155], v[128:131], v[168:171], v[152:155]
	v_mfma_f32_16x16x32_bf16 v[120:123], v[112:115], v[176:179], v[120:123]
	v_mfma_f32_16x16x32_bf16 v[116:119], v[128:131], v[176:179], v[116:119]
	v_mfma_f32_16x16x32_bf16 v[96:99], v[112:115], v[184:187], v[96:99]
	v_mfma_f32_16x16x32_bf16 v[92:95], v[128:131], v[184:187], v[92:95]
	v_mfma_f32_16x16x32_bf16 v[80:83], v[112:115], v[192:195], v[80:83]
	v_mfma_f32_16x16x32_bf16 v[76:79], v[128:131], v[192:195], v[76:79]
	s_setprio 0
	s_setprio 1
	v_mfma_f32_16x16x32_bf16 v[144:147], v[132:135], v[164:167], 0
	v_mfma_f32_16x16x32_bf16 v[136:139], v[148:151], v[164:167], 0
	v_mfma_f32_16x16x32_bf16 v[104:107], v[132:135], v[172:175], 0
	v_mfma_f32_16x16x32_bf16 v[100:103], v[148:151], v[172:175], 0
	v_mfma_f32_16x16x32_bf16 v[88:91], v[132:135], v[180:183], 0
	v_mfma_f32_16x16x32_bf16 v[84:87], v[148:151], v[180:183], 0
	v_mfma_f32_16x16x32_bf16 v[72:75], v[132:135], v[188:191], 0
	v_mfma_f32_16x16x32_bf16 v[68:71], v[148:151], v[188:191], 0
	v_mfma_f32_16x16x32_bf16 v[144:147], v[140:143], v[168:171], v[144:147]
	v_mfma_f32_16x16x32_bf16 v[136:139], v[156:159], v[168:171], v[136:139]
	v_mfma_f32_16x16x32_bf16 v[104:107], v[140:143], v[176:179], v[104:107]
	v_mfma_f32_16x16x32_bf16 v[100:103], v[156:159], v[176:179], v[100:103]
	v_mfma_f32_16x16x32_bf16 v[88:91], v[140:143], v[184:187], v[88:91]
	v_mfma_f32_16x16x32_bf16 v[84:87], v[156:159], v[184:187], v[84:87]
	v_mfma_f32_16x16x32_bf16 v[72:75], v[140:143], v[192:195], v[72:75]
	v_mfma_f32_16x16x32_bf16 v[68:71], v[156:159], v[192:195], v[68:71]
	s_setprio 0
	s_barrier
	s_add_u32 s30, s28, 0xfffc0080
	s_addc_u32 s31, s29, -1
	s_cmp_eq_u32 s45, 12
	s_cselect_b32 s35, s3, s31
	s_cselect_b32 s34, s17, s30
	s_cselect_b32 s31, s19, s44
	s_cselect_b32 s30, s25, s27
	v_lshl_add_u64 v[212:213], s[30:31], 0, v[202:203]
	s_add_i32 m0, s41, 0x10000
	ds_read_b128 v[164:167], v253 offset:16384
	ds_read_b128 v[168:171], v253 offset:17408
	ds_read_b128 v[172:175], v253 offset:18432
	ds_read_b128 v[176:179], v253 offset:19456
	ds_read_b128 v[180:183], v253 offset:20480
	ds_read_b128 v[184:187], v253 offset:21504
	ds_read_b128 v[188:191], v253 offset:22528
	ds_read_b128 v[192:195], v253 offset:23552
	global_load_lds_dwordx4 v[212:213], off
	s_add_i32 m0, s41, 0x12000
	s_add_u32 s52, s30, 0x40000
	v_lshl_add_u64 v[214:215], s[30:31], 0, v[206:207]
	s_addc_u32 s53, s31, 0
	global_load_lds_dwordx4 v[214:215], off
	v_lshl_add_u64 v[216:217], s[52:53], 0, v[202:203]
	s_add_i32 m0, s41, 0x14000
	v_lshl_add_u64 v[218:219], s[34:35], 0, v[204:205]
	global_load_lds_dwordx4 v[216:217], off
	s_add_i32 m0, s41, 0x16000
	v_lshl_add_u64 v[216:217], s[52:53], 0, v[206:207]
	global_load_lds_dwordx4 v[216:217], off
	v_lshl_add_u64 v[216:217], s[34:35], 0, v[0:1]
	s_waitcnt vmcnt(6) lgkmcnt(0)
	s_barrier
; #define PG8_MMA(ai, bj, At, Bt) do { __builtin_amdgcn_s_setprio(1); _Pragma("unroll") for (int m = 0; m < 4; ++m) _Pragma("unroll") for (int n = 0; n < 2; ++n) _Pragma("unroll") for (int k = 0; k < 2; ++k) \
;         acc[ai][bj][m][n] = __builtin_amdgcn_mfma_f32_16x16x32_bf16(Bt[n][k], At[m][k], acc[ai][bj][m][n], 0, 0, 0); __builtin_amdgcn_s_setprio(0); } while (0)
; #define PG8_WAIT_V(n) asm volatile("s_waitcnt vmcnt(" #n ")" ::: "memory")
; #define PG8_WAIT_L(n) asm volatile("s_waitcnt lgkmcnt(" #n ")" ::: "memory")
; #define PG8_BAR __builtin_amdgcn_s_barrier()
; #define PG8_SCHED __builtin_amdgcn_sched_barrier(0)
; template <class Epi, class Sched, bool ALIGN_EPI = false, bool SP2 = false>
; __device__ __forceinline__ void gemm_phase(PG8_LAS unsigned char* lds, const Gemm g, const Sched& S, const Epi& E) {
;     ...
;             PG8_WAIT_V(8); PG8_WAIT_L(0); PG8_BAR; PG8_MMA(1, 0, At, B0); PG8_MMA(1, 1, At, B1); PG8_BAR; PG8_SCHED;
	s_setprio 1
	v_mfma_f32_16x16x32_bf16 v[64:67], v[108:111], v[164:167], 0
	v_mfma_f32_16x16x32_bf16 v[60:63], v[124:127], v[164:167], 0
	v_mfma_f32_16x16x32_bf16 v[48:51], v[108:111], v[172:175], 0
	v_mfma_f32_16x16x32_bf16 v[44:47], v[124:127], v[172:175], 0
	v_mfma_f32_16x16x32_bf16 v[32:35], v[108:111], v[180:183], 0
	v_mfma_f32_16x16x32_bf16 v[28:31], v[124:127], v[180:183], 0
	v_mfma_f32_16x16x32_bf16 v[16:19], v[108:111], v[188:191], 0
	v_mfma_f32_16x16x32_bf16 v[12:15], v[124:127], v[188:191], 0
	v_mfma_f32_16x16x32_bf16 v[64:67], v[112:115], v[168:171], v[64:67]
	v_mfma_f32_16x16x32_bf16 v[60:63], v[128:131], v[168:171], v[60:63]
	v_mfma_f32_16x16x32_bf16 v[48:51], v[112:115], v[176:179], v[48:51]
	v_mfma_f32_16x16x32_bf16 v[44:47], v[128:131], v[176:179], v[44:47]
	v_mfma_f32_16x16x32_bf16 v[32:35], v[112:115], v[184:187], v[32:35]
	v_mfma_f32_16x16x32_bf16 v[28:31], v[128:131], v[184:187], v[28:31]
	v_mfma_f32_16x16x32_bf16 v[16:19], v[112:115], v[192:195], v[16:19]
	v_mfma_f32_16x16x32_bf16 v[12:15], v[128:131], v[192:195], v[12:15]
	s_setprio 0
	s_setprio 1
	v_mfma_f32_16x16x32_bf16 v[56:59], v[132:135], v[164:167], 0
	v_mfma_f32_16x16x32_bf16 v[52:55], v[148:151], v[164:167], 0
	v_mfma_f32_16x16x32_bf16 v[40:43], v[132:135], v[172:175], 0
	v_mfma_f32_16x16x32_bf16 v[36:39], v[148:151], v[172:175], 0
	v_mfma_f32_16x16x32_bf16 v[24:27], v[132:135], v[180:183], 0
	v_mfma_f32_16x16x32_bf16 v[20:23], v[148:151], v[180:183], 0
	v_mfma_f32_16x16x32_bf16 v[8:11], v[132:135], v[188:191], 0
	v_mfma_f32_16x16x32_bf16 v[4:7], v[148:151], v[188:191], 0
	v_mfma_f32_16x16x32_bf16 v[56:59], v[140:143], v[168:171], v[56:59]
	v_mfma_f32_16x16x32_bf16 v[52:55], v[156:159], v[168:171], v[52:55]
	v_mfma_f32_16x16x32_bf16 v[40:43], v[140:143], v[176:179], v[40:43]
	v_mfma_f32_16x16x32_bf16 v[36:39], v[156:159], v[176:179], v[36:39]
	v_mfma_f32_16x16x32_bf16 v[24:27], v[140:143], v[184:187], v[24:27]
	v_mfma_f32_16x16x32_bf16 v[20:23], v[156:159], v[184:187], v[20:23]
	v_mfma_f32_16x16x32_bf16 v[8:11], v[140:143], v[192:195], v[8:11]
	v_mfma_f32_16x16x32_bf16 v[4:7], v[156:159], v[192:195], v[4:7]
	s_setprio 0
	s_barrier
	s_branch .Lkmid_1
; #define PG8_STAGE(bufoff, gbase, voff) do { _Pragma("unroll") for (int _i = 0; _i < 2; ++_i) \
;         __builtin_amdgcn_global_load_lds((const unsigned*)((const char*)(gbase) + (voff)[_i]), (PG8_LAS unsigned*)(lds + (bufoff) + ldsw + _i * 8192), 16, 0, 0); } while (0)
; #define PG8_LDA(dst, b, h) do { _Pragma("unroll") for (int m = 0; m < 4; ++m) _Pragma("unroll") for (int k = 0; k < 2; ++k) dst[m][k] = *(const PG8_LAS bf16x8*)(lds + PG8_SA(b, h) + aoff + m * 2048 + k * 1024); } while (0)
; #define PG8_LDB(dst, b, h) do { _Pragma("unroll") for (int n = 0; n < 2; ++n) _Pragma("unroll") for (int k = 0; k < 2; ++k) dst[n][k] = *(const PG8_LAS bf16x8*)(lds + PG8_SB(b, h) + boff + n * 2048 + k * 1024); } while (0)
; #define PG8_MMA(ai, bj, At, Bt) do { __builtin_amdgcn_s_setprio(1); _Pragma("unroll") for (int m = 0; m < 4; ++m) _Pragma("unroll") for (int n = 0; n < 2; ++n) _Pragma("unroll") for (int k = 0; k < 2; ++k) \
;         acc[ai][bj][m][n] = __builtin_amdgcn_mfma_f32_16x16x32_bf16(Bt[n][k], At[m][k], acc[ai][bj][m][n], 0, 0, 0); __builtin_amdgcn_s_setprio(0); } while (0)
; #define PG8_WAIT_V(n) asm volatile("s_waitcnt vmcnt(" #n ")" ::: "memory")
; #define PG8_WAIT_L(n) asm volatile("s_waitcnt lgkmcnt(" #n ")" ::: "memory")
; template <class Epi, class Sched, bool ALIGN_EPI = false, bool SP2 = false>
; __device__ __forceinline__ void gemm_phase(PG8_LAS unsigned char* lds, const Gemm g, const Sched& S, const Epi& E) {
;     ...
;             const bool last = (t == nt - 2);
;             const char* a1 = cA + (size_t)(t + 1) * kstep;
;             const char* a2 = last ? nA : cA + (size_t)(t + 2) * kstep; const char* b2 = last ? nB : cB + (size_t)(t + 2) * kstep;
;             const char* a3 = a2 + kstep; const char* b3 = b2 + kstep;
;             if (last && has_next) S.a_ready(nxt);
;             if constexpr (SP2) {
;             PG8_LDB(B0, 0, 0); PG8_LDB(B1, 0, 1); PG8_SCHED; PG8_LDA(At, 0, 0); PG8_STAGE(PG8_SA(1, 1), a1 + hstep, voffA);
;             PG8_WAIT_V(8); PG8_WAIT_L(0); PG8_BAR; PG8_MMA(0, 0, At, B0); PG8_MMA(0, 1, At, B1); PG8_BAR; PG8_SCHED;
;             PG8_LDA(At, 0, 1); PG8_STAGE(PG8_SB(0, 0), b2, voffB); PG8_STAGE(PG8_SB(0, 1), b2 + hstep, voffB); PG8_STAGE(PG8_SA(0, 0), a2, voffA);
;             PG8_WAIT_V(8); PG8_WAIT_L(0); PG8_BAR; PG8_MMA(1, 0, At, B0); PG8_MMA(1, 1, At, B1); PG8_BAR; PG8_SCHED;
.LBB0_329:
	s_add_i32 m0, s49, 0xffffff80
	ds_read_b128 v[108:111], v251
	ds_read_b128 v[112:115], v251 offset:1024
	ds_read_b128 v[124:127], v251 offset:2048
	ds_read_b128 v[128:131], v251 offset:3072
	ds_read_b128 v[132:135], v251 offset:16384
	ds_read_b128 v[140:143], v251 offset:17408
	ds_read_b128 v[148:151], v251 offset:18432
	ds_read_b128 v[156:159], v251 offset:19456
	global_load_lds_dwordx4 v[216:217], off offset:128
	s_add_i32 m0, s50, 0xffffff80
	v_lshl_add_u64 v[212:213], s[28:29], 0, v[208:209]
	global_load_lds_dwordx4 v[218:219], off offset:128
	s_add_i32 m0, s42, 0xc000
	ds_read_b128 v[164:167], v253
	ds_read_b128 v[168:171], v253 offset:1024
	ds_read_b128 v[172:175], v253 offset:2048
	ds_read_b128 v[176:179], v253 offset:3072
	ds_read_b128 v[180:183], v253 offset:4096
	ds_read_b128 v[184:187], v253 offset:5120
	ds_read_b128 v[188:191], v253 offset:6144
	ds_read_b128 v[192:195], v253 offset:7168
	global_load_lds_dwordx4 v[212:213], off
	s_add_i32 m0, s42, 0xe000
	v_lshl_add_u64 v[212:213], s[28:29], 0, v[210:211]
	global_load_lds_dwordx4 v[212:213], off
	s_waitcnt vmcnt(8) lgkmcnt(0)
	s_barrier
	s_setprio 1
	v_mfma_f32_16x16x32_bf16 v[160:163], v[108:111], v[164:167], v[160:163]
	v_mfma_f32_16x16x32_bf16 v[152:155], v[124:127], v[164:167], v[152:155]
	v_mfma_f32_16x16x32_bf16 v[120:123], v[108:111], v[172:175], v[120:123]
	v_mfma_f32_16x16x32_bf16 v[116:119], v[124:127], v[172:175], v[116:119]
	v_mfma_f32_16x16x32_bf16 v[96:99], v[108:111], v[180:183], v[96:99]
	v_mfma_f32_16x16x32_bf16 v[92:95], v[124:127], v[180:183], v[92:95]
	v_mfma_f32_16x16x32_bf16 v[80:83], v[108:111], v[188:191], v[80:83]
	v_mfma_f32_16x16x32_bf16 v[76:79], v[124:127], v[188:191], v[76:79]
	v_mfma_f32_16x16x32_bf16 v[160:163], v[112:115], v[168:171], v[160:163]
	v_mfma_f32_16x16x32_bf16 v[152:155], v[128:131], v[168:171], v[152:155]
	v_mfma_f32_16x16x32_bf16 v[120:123], v[112:115], v[176:179], v[120:123]
	v_mfma_f32_16x16x32_bf16 v[116:119], v[128:131], v[176:179], v[116:119]
	v_mfma_f32_16x16x32_bf16 v[96:99], v[112:115], v[184:187], v[96:99]
	v_mfma_f32_16x16x32_bf16 v[92:95], v[128:131], v[184:187], v[92:95]
	v_mfma_f32_16x16x32_bf16 v[80:83], v[112:115], v[192:195], v[80:83]
	v_mfma_f32_16x16x32_bf16 v[76:79], v[128:131], v[192:195], v[76:79]
	s_setprio 0
	s_setprio 1
	v_mfma_f32_16x16x32_bf16 v[144:147], v[132:135], v[164:167], v[144:147]
	v_mfma_f32_16x16x32_bf16 v[136:139], v[148:151], v[164:167], v[136:139]
	v_mfma_f32_16x16x32_bf16 v[104:107], v[132:135], v[172:175], v[104:107]
	v_mfma_f32_16x16x32_bf16 v[100:103], v[148:151], v[172:175], v[100:103]
	v_mfma_f32_16x16x32_bf16 v[88:91], v[132:135], v[180:183], v[88:91]
	v_mfma_f32_16x16x32_bf16 v[84:87], v[148:151], v[180:183], v[84:87]
	v_mfma_f32_16x16x32_bf16 v[72:75], v[132:135], v[188:191], v[72:75]
	v_mfma_f32_16x16x32_bf16 v[68:71], v[148:151], v[188:191], v[68:71]
	v_mfma_f32_16x16x32_bf16 v[144:147], v[140:143], v[168:171], v[144:147]
	v_mfma_f32_16x16x32_bf16 v[136:139], v[156:159], v[168:171], v[136:139]
	v_mfma_f32_16x16x32_bf16 v[104:107], v[140:143], v[176:179], v[104:107]
	v_mfma_f32_16x16x32_bf16 v[100:103], v[156:159], v[176:179], v[100:103]
	v_mfma_f32_16x16x32_bf16 v[88:91], v[140:143], v[184:187], v[88:91]
	v_mfma_f32_16x16x32_bf16 v[84:87], v[156:159], v[184:187], v[84:87]
	v_mfma_f32_16x16x32_bf16 v[72:75], v[140:143], v[192:195], v[72:75]
	v_mfma_f32_16x16x32_bf16 v[68:71], v[156:159], v[192:195], v[68:71]
	s_setprio 0
	s_barrier
	s_add_u32 s30, s28, 0xfffc0080
	s_addc_u32 s31, s29, -1
	s_cmp_eq_u32 s45, 12
	s_cselect_b32 s35, s3, s31
	s_cselect_b32 s34, s17, s30
	s_cselect_b32 s31, s19, s44
	s_cselect_b32 s30, s25, s27
	v_lshl_add_u64 v[212:213], s[30:31], 0, v[202:203]
	s_add_i32 m0, s41, 0x10000
	ds_read_b128 v[164:167], v253 offset:16384
	ds_read_b128 v[168:171], v253 offset:17408
	ds_read_b128 v[172:175], v253 offset:18432
	ds_read_b128 v[176:179], v253 offset:19456
	ds_read_b128 v[180:183], v253 offset:20480
	ds_read_b128 v[184:187], v253 offset:21504
	ds_read_b128 v[188:191], v253 offset:22528
	ds_read_b128 v[192:195], v253 offset:23552
	global_load_lds_dwordx4 v[212:213], off
	s_add_i32 m0, s41, 0x12000
	s_add_u32 s52, s30, 0x40000
	v_lshl_add_u64 v[214:215], s[30:31], 0, v[206:207]
	s_addc_u32 s53, s31, 0
	global_load_lds_dwordx4 v[214:215], off
	v_lshl_add_u64 v[216:217], s[52:53], 0, v[202:203]
	s_add_i32 m0, s41, 0x14000
	v_lshl_add_u64 v[218:219], s[34:35], 0, v[204:205]
	global_load_lds_dwordx4 v[216:217], off
	s_add_i32 m0, s41, 0x16000
	v_lshl_add_u64 v[216:217], s[52:53], 0, v[206:207]
	global_load_lds_dwordx4 v[216:217], off
	v_lshl_add_u64 v[216:217], s[34:35], 0, v[0:1]
	s_waitcnt vmcnt(6) lgkmcnt(0)
	s_barrier
	s_setprio 1
	v_mfma_f32_16x16x32_bf16 v[64:67], v[108:111], v[164:167], v[64:67]
	v_mfma_f32_16x16x32_bf16 v[60:63], v[124:127], v[164:167], v[60:63]
	v_mfma_f32_16x16x32_bf16 v[48:51], v[108:111], v[172:175], v[48:51]
	v_mfma_f32_16x16x32_bf16 v[44:47], v[124:127], v[172:175], v[44:47]
	v_mfma_f32_16x16x32_bf16 v[32:35], v[108:111], v[180:183], v[32:35]
	v_mfma_f32_16x16x32_bf16 v[28:31], v[124:127], v[180:183], v[28:31]
	v_mfma_f32_16x16x32_bf16 v[16:19], v[108:111], v[188:191], v[16:19]
	v_mfma_f32_16x16x32_bf16 v[12:15], v[124:127], v[188:191], v[12:15]
	v_mfma_f32_16x16x32_bf16 v[64:67], v[112:115], v[168:171], v[64:67]
	v_mfma_f32_16x16x32_bf16 v[60:63], v[128:131], v[168:171], v[60:63]
	v_mfma_f32_16x16x32_bf16 v[48:51], v[112:115], v[176:179], v[48:51]
	v_mfma_f32_16x16x32_bf16 v[44:47], v[128:131], v[176:179], v[44:47]
	v_mfma_f32_16x16x32_bf16 v[32:35], v[112:115], v[184:187], v[32:35]
	v_mfma_f32_16x16x32_bf16 v[28:31], v[128:131], v[184:187], v[28:31]
	v_mfma_f32_16x16x32_bf16 v[16:19], v[112:115], v[192:195], v[16:19]
	v_mfma_f32_16x16x32_bf16 v[12:15], v[128:131], v[192:195], v[12:15]
	s_setprio 0
	s_setprio 1
	v_mfma_f32_16x16x32_bf16 v[56:59], v[132:135], v[164:167], v[56:59]
	v_mfma_f32_16x16x32_bf16 v[52:55], v[148:151], v[164:167], v[52:55]
	v_mfma_f32_16x16x32_bf16 v[40:43], v[132:135], v[172:175], v[40:43]
	v_mfma_f32_16x16x32_bf16 v[36:39], v[148:151], v[172:175], v[36:39]
	v_mfma_f32_16x16x32_bf16 v[24:27], v[132:135], v[180:183], v[24:27]
	v_mfma_f32_16x16x32_bf16 v[20:23], v[148:151], v[180:183], v[20:23]
	v_mfma_f32_16x16x32_bf16 v[8:11], v[132:135], v[188:191], v[8:11]
	v_mfma_f32_16x16x32_bf16 v[4:7], v[148:151], v[188:191], v[4:7]
	v_mfma_f32_16x16x32_bf16 v[56:59], v[140:143], v[168:171], v[56:59]
	v_mfma_f32_16x16x32_bf16 v[52:55], v[156:159], v[168:171], v[52:55]
	v_mfma_f32_16x16x32_bf16 v[40:43], v[140:143], v[176:179], v[40:43]
	v_mfma_f32_16x16x32_bf16 v[36:39], v[156:159], v[176:179], v[36:39]
	v_mfma_f32_16x16x32_bf16 v[24:27], v[140:143], v[184:187], v[24:27]
	v_mfma_f32_16x16x32_bf16 v[20:23], v[156:159], v[184:187], v[20:23]
	v_mfma_f32_16x16x32_bf16 v[8:11], v[140:143], v[192:195], v[8:11]
	v_mfma_f32_16x16x32_bf16 v[4:7], v[156:159], v[192:195], v[4:7]
	s_setprio 0
	s_barrier

; #define PG8_STAGE(bufoff, gbase, voff) do { _Pragma("unroll") for (int _i = 0; _i < 2; ++_i) \
;         __builtin_amdgcn_global_load_lds((const unsigned*)((const char*)(gbase) + (voff)[_i]), (PG8_LAS unsigned*)(lds + (bufoff) + ldsw + _i * 8192), 16, 0, 0); } while (0)
; #define PG8_LDA(dst, b, h) do { _Pragma("unroll") for (int m = 0; m < 4; ++m) _Pragma("unroll") for (int k = 0; k < 2; ++k) dst[m][k] = *(const PG8_LAS bf16x8*)(lds + PG8_SA(b, h) + aoff + m * 2048 + k * 1024); } while (0)
; #define PG8_LDB(dst, b, h) do { _Pragma("unroll") for (int n = 0; n < 2; ++n) _Pragma("unroll") for (int k = 0; k < 2; ++k) dst[n][k] = *(const PG8_LAS bf16x8*)(lds + PG8_SB(b, h) + boff + n * 2048 + k * 1024); } while (0)
; #define PG8_WAIT_V(n) asm volatile("s_waitcnt vmcnt(" #n ")" ::: "memory")
; #define PG8_WAIT_L(n) asm volatile("s_waitcnt lgkmcnt(" #n ")" ::: "memory")
; #define PG8_BAR __builtin_amdgcn_s_barrier()
; #define PG8_SCHED __builtin_amdgcn_sched_barrier(0)
; template <class Epi, class Sched, bool ALIGN_EPI = false, bool SP2 = false>
; __device__ __forceinline__ void gemm_phase(PG8_LAS unsigned char* lds, const Gemm g, const Sched& S, const Epi& E) {
;     ...
;         const bool has_next = S.next(ui + 1, nxt);
;         const char* nA = has_next ? (const char*)g.A + (size_t)nxt.pm * tstep : cA; const char* nB = has_next ? (const char*)g.Bt + (size_t)nxt.pn * tstep : cB;
;         for (int t = 0; t < nt; t += 2) {
;             const bool last = (t == nt - 2);
;             const char* a1 = cA + (size_t)(t + 1) * kstep;
;             const char* a2 = last ? nA : cA + (size_t)(t + 2) * kstep; const char* b2 = last ? nB : cB + (size_t)(t + 2) * kstep;
;             const char* a3 = a2 + kstep; const char* b3 = b2 + kstep;
;             if (last && has_next) S.a_ready(nxt);
;             if constexpr (SP2) {
;             PG8_LDB(B0, 0, 0); PG8_LDB(B1, 0, 1); PG8_SCHED; PG8_LDA(At, 0, 0); PG8_STAGE(PG8_SA(1, 1), a1 + hstep, voffA);
;             PG8_WAIT_V(8); PG8_WAIT_L(0); PG8_BAR; PG8_MMA(0, 0, At, B0); PG8_MMA(0, 1, At, B1); PG8_BAR; PG8_SCHED;
;             PG8_LDA(At, 0, 1); PG8_STAGE(PG8_SB(0, 0), b2, voffB); PG8_STAGE(PG8_SB(0, 1), b2 + hstep, voffB); PG8_STAGE(PG8_SA(0, 0), a2, voffA);
;             PG8_WAIT_V(8); PG8_WAIT_L(0); PG8_BAR; PG8_MMA(1, 0, At, B0); PG8_MMA(1, 1, At, B1); PG8_BAR; PG8_SCHED;
.LBB0_404:
	s_ashr_i32 s17, s16, 31
	s_lshl_b64 s[20:21], s[16:17], 19
	s_add_u32 s20, s29, s20
	s_addc_u32 s21, s30, s21
	s_and_b64 s[22:23], s[4:5], exec
	s_cselect_b32 s7, s21, s9
	s_cselect_b32 s17, s20, s8
	s_ashr_i32 s19, s18, 31
	s_lshl_b64 s[22:23], s[18:19], 19
	s_add_u32 s22, s31, s22
	s_addc_u32 s23, s34, s23
	s_and_b64 s[26:27], s[4:5], exec
	s_cselect_b32 s19, s23, s25
	s_cselect_b32 s43, s22, s24
	s_add_u32 s8, s8, 0x40080
	s_addc_u32 s9, s9, 0
	s_add_u32 s44, s24, 0x100
	s_addc_u32 s45, s25, 0
	s_mov_b32 s46, -2
	s_add_i32 s50, 0, 0x14000
	ds_read_b128 v[144:147], v164
	ds_read_b128 v[148:151], v164 offset:1024
	ds_read_b128 v[152:155], v164 offset:2048
	ds_read_b128 v[156:159], v164 offset:3072
	ds_read_b128 v[160:163], v164 offset:16384
	ds_read_b128 v[168:171], v164 offset:17408
	ds_read_b128 v[172:175], v164 offset:18432
	ds_read_b128 v[176:179], v164 offset:19456
	v_lshl_add_u64 v[198:199], s[8:9], 0, v[140:141]
	s_add_i32 m0, s37, 0xc000
	ds_read_b128 v[180:183], v166
	ds_read_b128 v[184:187], v166 offset:1024
	ds_read_b128 v[188:191], v166 offset:2048
	ds_read_b128 v[192:195], v166 offset:3072
	ds_read_b128 v[202:205], v166 offset:4096
	ds_read_b128 v[206:209], v166 offset:5120
	ds_read_b128 v[210:213], v166 offset:6144
	ds_read_b128 v[214:217], v166 offset:7168
	global_load_lds_dwordx4 v[198:199], off
	s_add_i32 m0, s37, 0xe000
	v_lshl_add_u64 v[198:199], s[8:9], 0, v[142:143]
	global_load_lds_dwordx4 v[198:199], off
	s_waitcnt vmcnt(8) lgkmcnt(0)
	s_barrier
	s_setprio 1
	v_mfma_f32_16x16x32_bf16 v[128:131], v[144:147], v[180:183], 0
	v_mfma_f32_16x16x32_bf16 v[120:123], v[152:155], v[180:183], 0
	v_mfma_f32_16x16x32_bf16 v[112:115], v[144:147], v[188:191], 0
	v_mfma_f32_16x16x32_bf16 v[104:107], v[152:155], v[188:191], 0
	v_mfma_f32_16x16x32_bf16 v[96:99], v[144:147], v[202:205], 0
	v_mfma_f32_16x16x32_bf16 v[88:91], v[152:155], v[202:205], 0
	v_mfma_f32_16x16x32_bf16 v[80:83], v[144:147], v[210:213], 0
	v_mfma_f32_16x16x32_bf16 v[72:75], v[152:155], v[210:213], 0
	v_mfma_f32_16x16x32_bf16 v[128:131], v[148:151], v[184:187], v[128:131]
	v_mfma_f32_16x16x32_bf16 v[120:123], v[156:159], v[184:187], v[120:123]
	v_mfma_f32_16x16x32_bf16 v[112:115], v[148:151], v[192:195], v[112:115]
	v_mfma_f32_16x16x32_bf16 v[104:107], v[156:159], v[192:195], v[104:107]
	v_mfma_f32_16x16x32_bf16 v[96:99], v[148:151], v[206:209], v[96:99]
	v_mfma_f32_16x16x32_bf16 v[88:91], v[156:159], v[206:209], v[88:91]
	v_mfma_f32_16x16x32_bf16 v[80:83], v[148:151], v[214:217], v[80:83]
	v_mfma_f32_16x16x32_bf16 v[72:75], v[156:159], v[214:217], v[72:75]
	s_setprio 0
	s_setprio 1
	v_mfma_f32_16x16x32_bf16 v[124:127], v[160:163], v[180:183], 0
	v_mfma_f32_16x16x32_bf16 v[116:119], v[172:175], v[180:183], 0
	v_mfma_f32_16x16x32_bf16 v[108:111], v[160:163], v[188:191], 0
	v_mfma_f32_16x16x32_bf16 v[100:103], v[172:175], v[188:191], 0
	v_mfma_f32_16x16x32_bf16 v[92:95], v[160:163], v[202:205], 0
	v_mfma_f32_16x16x32_bf16 v[84:87], v[172:175], v[202:205], 0
	v_mfma_f32_16x16x32_bf16 v[76:79], v[160:163], v[210:213], 0
	v_mfma_f32_16x16x32_bf16 v[68:71], v[172:175], v[210:213], 0
	v_mfma_f32_16x16x32_bf16 v[124:127], v[168:171], v[184:187], v[124:127]
	v_mfma_f32_16x16x32_bf16 v[116:119], v[176:179], v[184:187], v[116:119]
	v_mfma_f32_16x16x32_bf16 v[108:111], v[168:171], v[192:195], v[108:111]
	v_mfma_f32_16x16x32_bf16 v[100:103], v[176:179], v[192:195], v[100:103]
	v_mfma_f32_16x16x32_bf16 v[92:95], v[168:171], v[206:209], v[92:95]
	v_mfma_f32_16x16x32_bf16 v[84:87], v[176:179], v[206:209], v[84:87]
	v_mfma_f32_16x16x32_bf16 v[76:79], v[168:171], v[214:217], v[76:79]
	v_mfma_f32_16x16x32_bf16 v[68:71], v[176:179], v[214:217], v[68:71]
	s_setprio 0
	s_barrier
	s_add_u32 s24, s8, 0xfffc0080
	s_addc_u32 s25, s9, -1
	s_cmp_eq_u32 s46, 12
	s_cselect_b32 s27, s7, s25
	s_cselect_b32 s26, s17, s24
	s_cselect_b32 s25, s19, s45
	s_cselect_b32 s24, s43, s44
	v_lshl_add_u64 v[198:199], s[24:25], 0, v[134:135]
	s_add_i32 m0, s35, 0x10000
	ds_read_b128 v[180:183], v166 offset:16384
	ds_read_b128 v[184:187], v166 offset:17408
	ds_read_b128 v[188:191], v166 offset:18432
	ds_read_b128 v[192:195], v166 offset:19456
	ds_read_b128 v[202:205], v166 offset:20480
	ds_read_b128 v[206:209], v166 offset:21504
	ds_read_b128 v[210:213], v166 offset:22528
	ds_read_b128 v[214:217], v166 offset:23552
	global_load_lds_dwordx4 v[198:199], off
	s_add_i32 m0, s35, 0x12000
	s_add_u32 s48, s24, 0x40000
	v_lshl_add_u64 v[218:219], s[24:25], 0, v[0:1]
	s_addc_u32 s49, s25, 0
	global_load_lds_dwordx4 v[218:219], off
	v_lshl_add_u64 v[220:221], s[48:49], 0, v[134:135]
	s_add_i32 m0, s35, 0x14000
	v_lshl_add_u64 v[222:223], s[26:27], 0, v[132:133]
	global_load_lds_dwordx4 v[220:221], off
	s_add_i32 m0, s35, 0x16000
	v_lshl_add_u64 v[220:221], s[48:49], 0, v[0:1]
	global_load_lds_dwordx4 v[220:221], off
	v_lshl_add_u64 v[220:221], s[26:27], 0, v[136:137]
	s_waitcnt vmcnt(6) lgkmcnt(0)
	s_barrier
; #define PG8_MMA(ai, bj, At, Bt) do { __builtin_amdgcn_s_setprio(1); _Pragma("unroll") for (int m = 0; m < 4; ++m) _Pragma("unroll") for (int n = 0; n < 2; ++n) _Pragma("unroll") for (int k = 0; k < 2; ++k) \
;         acc[ai][bj][m][n] = __builtin_amdgcn_mfma_f32_16x16x32_bf16(Bt[n][k], At[m][k], acc[ai][bj][m][n], 0, 0, 0); __builtin_amdgcn_s_setprio(0); } while (0)
; #define PG8_WAIT_V(n) asm volatile("s_waitcnt vmcnt(" #n ")" ::: "memory")
; #define PG8_WAIT_L(n) asm volatile("s_waitcnt lgkmcnt(" #n ")" ::: "memory")
; #define PG8_BAR __builtin_amdgcn_s_barrier()
; #define PG8_SCHED __builtin_amdgcn_sched_barrier(0)
; template <class Epi, class Sched, bool ALIGN_EPI = false, bool SP2 = false>
; __device__ __forceinline__ void gemm_phase(PG8_LAS unsigned char* lds, const Gemm g, const Sched& S, const Epi& E) {
;     ...
;             PG8_WAIT_V(8); PG8_WAIT_L(0); PG8_BAR; PG8_MMA(1, 0, At, B0); PG8_MMA(1, 1, At, B1); PG8_BAR; PG8_SCHED;
	s_setprio 1
	v_mfma_f32_16x16x32_bf16 v[64:67], v[144:147], v[180:183], 0
	v_mfma_f32_16x16x32_bf16 v[56:59], v[152:155], v[180:183], 0
	v_mfma_f32_16x16x32_bf16 v[48:51], v[144:147], v[188:191], 0
	v_mfma_f32_16x16x32_bf16 v[40:43], v[152:155], v[188:191], 0
	v_mfma_f32_16x16x32_bf16 v[32:35], v[144:147], v[202:205], 0
	v_mfma_f32_16x16x32_bf16 v[24:27], v[152:155], v[202:205], 0
	v_mfma_f32_16x16x32_bf16 v[16:19], v[144:147], v[210:213], 0
	v_mfma_f32_16x16x32_bf16 v[8:11], v[152:155], v[210:213], 0
	v_mfma_f32_16x16x32_bf16 v[64:67], v[148:151], v[184:187], v[64:67]
	v_mfma_f32_16x16x32_bf16 v[56:59], v[156:159], v[184:187], v[56:59]
	v_mfma_f32_16x16x32_bf16 v[48:51], v[148:151], v[192:195], v[48:51]
	v_mfma_f32_16x16x32_bf16 v[40:43], v[156:159], v[192:195], v[40:43]
	v_mfma_f32_16x16x32_bf16 v[32:35], v[148:151], v[206:209], v[32:35]
	v_mfma_f32_16x16x32_bf16 v[24:27], v[156:159], v[206:209], v[24:27]
	v_mfma_f32_16x16x32_bf16 v[16:19], v[148:151], v[214:217], v[16:19]
	v_mfma_f32_16x16x32_bf16 v[8:11], v[156:159], v[214:217], v[8:11]
	s_setprio 0
	s_setprio 1
	v_mfma_f32_16x16x32_bf16 v[60:63], v[160:163], v[180:183], 0
	v_mfma_f32_16x16x32_bf16 v[52:55], v[172:175], v[180:183], 0
	v_mfma_f32_16x16x32_bf16 v[44:47], v[160:163], v[188:191], 0
	v_mfma_f32_16x16x32_bf16 v[36:39], v[172:175], v[188:191], 0
	v_mfma_f32_16x16x32_bf16 v[28:31], v[160:163], v[202:205], 0
	v_mfma_f32_16x16x32_bf16 v[20:23], v[172:175], v[202:205], 0
	v_mfma_f32_16x16x32_bf16 v[12:15], v[160:163], v[210:213], 0
	v_mfma_f32_16x16x32_bf16 v[4:7], v[172:175], v[210:213], 0
	v_mfma_f32_16x16x32_bf16 v[60:63], v[168:171], v[184:187], v[60:63]
	v_mfma_f32_16x16x32_bf16 v[52:55], v[176:179], v[184:187], v[52:55]
	v_mfma_f32_16x16x32_bf16 v[44:47], v[168:171], v[192:195], v[44:47]
	v_mfma_f32_16x16x32_bf16 v[36:39], v[176:179], v[192:195], v[36:39]
	v_mfma_f32_16x16x32_bf16 v[28:31], v[168:171], v[206:209], v[28:31]
	v_mfma_f32_16x16x32_bf16 v[20:23], v[176:179], v[206:209], v[20:23]
	v_mfma_f32_16x16x32_bf16 v[12:15], v[168:171], v[214:217], v[12:15]
	v_mfma_f32_16x16x32_bf16 v[4:7], v[176:179], v[214:217], v[4:7]
	s_setprio 0
	s_barrier
	s_branch .Lkmid_2
; #define PG8_STAGE(bufoff, gbase, voff) do { _Pragma("unroll") for (int _i = 0; _i < 2; ++_i) \
;         __builtin_amdgcn_global_load_lds((const unsigned*)((const char*)(gbase) + (voff)[_i]), (PG8_LAS unsigned*)(lds + (bufoff) + ldsw + _i * 8192), 16, 0, 0); } while (0)
; #define PG8_LDA(dst, b, h) do { _Pragma("unroll") for (int m = 0; m < 4; ++m) _Pragma("unroll") for (int k = 0; k < 2; ++k) dst[m][k] = *(const PG8_LAS bf16x8*)(lds + PG8_SA(b, h) + aoff + m * 2048 + k * 1024); } while (0)
; #define PG8_LDB(dst, b, h) do { _Pragma("unroll") for (int n = 0; n < 2; ++n) _Pragma("unroll") for (int k = 0; k < 2; ++k) dst[n][k] = *(const PG8_LAS bf16x8*)(lds + PG8_SB(b, h) + boff + n * 2048 + k * 1024); } while (0)
; #define PG8_MMA(ai, bj, At, Bt) do { __builtin_amdgcn_s_setprio(1); _Pragma("unroll") for (int m = 0; m < 4; ++m) _Pragma("unroll") for (int n = 0; n < 2; ++n) _Pragma("unroll") for (int k = 0; k < 2; ++k) \
;         acc[ai][bj][m][n] = __builtin_amdgcn_mfma_f32_16x16x32_bf16(Bt[n][k], At[m][k], acc[ai][bj][m][n], 0, 0, 0); __builtin_amdgcn_s_setprio(0); } while (0)
; #define PG8_WAIT_V(n) asm volatile("s_waitcnt vmcnt(" #n ")" ::: "memory")
; #define PG8_WAIT_L(n) asm volatile("s_waitcnt lgkmcnt(" #n ")" ::: "memory")
; template <class Epi, class Sched, bool ALIGN_EPI = false, bool SP2 = false>
; __device__ __forceinline__ void gemm_phase(PG8_LAS unsigned char* lds, const Gemm g, const Sched& S, const Epi& E) {
;     ...
;             const bool last = (t == nt - 2);
;             const char* a1 = cA + (size_t)(t + 1) * kstep;
;             const char* a2 = last ? nA : cA + (size_t)(t + 2) * kstep; const char* b2 = last ? nB : cB + (size_t)(t + 2) * kstep;
;             const char* a3 = a2 + kstep; const char* b3 = b2 + kstep;
;             if (last && has_next) S.a_ready(nxt);
;             if constexpr (SP2) {
;             PG8_LDB(B0, 0, 0); PG8_LDB(B1, 0, 1); PG8_SCHED; PG8_LDA(At, 0, 0); PG8_STAGE(PG8_SA(1, 1), a1 + hstep, voffA);
;             PG8_WAIT_V(8); PG8_WAIT_L(0); PG8_BAR; PG8_MMA(0, 0, At, B0); PG8_MMA(0, 1, At, B1); PG8_BAR; PG8_SCHED;
;             PG8_LDA(At, 0, 1); PG8_STAGE(PG8_SB(0, 0), b2, voffB); PG8_STAGE(PG8_SB(0, 1), b2 + hstep, voffB); PG8_STAGE(PG8_SA(0, 0), a2, voffA);
;             PG8_WAIT_V(8); PG8_WAIT_L(0); PG8_BAR; PG8_MMA(1, 0, At, B0); PG8_MMA(1, 1, At, B1); PG8_BAR; PG8_SCHED;
.LBB0_405:
	s_add_i32 m0, s41, 0xffffff80
	s_add_i32 s50, 0, 0x14000
	ds_read_b128 v[144:147], v164
	ds_read_b128 v[148:151], v164 offset:1024
	ds_read_b128 v[152:155], v164 offset:2048
	ds_read_b128 v[156:159], v164 offset:3072
	ds_read_b128 v[160:163], v164 offset:16384
	ds_read_b128 v[168:171], v164 offset:17408
	ds_read_b128 v[172:175], v164 offset:18432
	ds_read_b128 v[176:179], v164 offset:19456
	global_load_lds_dwordx4 v[220:221], off offset:128
	s_add_i32 m0, s42, 0xffffff80
	v_lshl_add_u64 v[198:199], s[8:9], 0, v[140:141]
	global_load_lds_dwordx4 v[222:223], off offset:128
	s_add_i32 m0, s37, 0xc000
	ds_read_b128 v[180:183], v166
	ds_read_b128 v[184:187], v166 offset:1024
	ds_read_b128 v[188:191], v166 offset:2048
	ds_read_b128 v[192:195], v166 offset:3072
	ds_read_b128 v[202:205], v166 offset:4096
	ds_read_b128 v[206:209], v166 offset:5120
	ds_read_b128 v[210:213], v166 offset:6144
	ds_read_b128 v[214:217], v166 offset:7168
	global_load_lds_dwordx4 v[198:199], off
	s_add_i32 m0, s37, 0xe000
	v_lshl_add_u64 v[198:199], s[8:9], 0, v[142:143]
	global_load_lds_dwordx4 v[198:199], off
	s_waitcnt vmcnt(8) lgkmcnt(0)
	s_barrier
	s_setprio 1
	v_mfma_f32_16x16x32_bf16 v[128:131], v[144:147], v[180:183], v[128:131]
	v_mfma_f32_16x16x32_bf16 v[120:123], v[152:155], v[180:183], v[120:123]
	v_mfma_f32_16x16x32_bf16 v[112:115], v[144:147], v[188:191], v[112:115]
	v_mfma_f32_16x16x32_bf16 v[104:107], v[152:155], v[188:191], v[104:107]
	v_mfma_f32_16x16x32_bf16 v[96:99], v[144:147], v[202:205], v[96:99]
	v_mfma_f32_16x16x32_bf16 v[88:91], v[152:155], v[202:205], v[88:91]
	v_mfma_f32_16x16x32_bf16 v[80:83], v[144:147], v[210:213], v[80:83]
	v_mfma_f32_16x16x32_bf16 v[72:75], v[152:155], v[210:213], v[72:75]
	v_mfma_f32_16x16x32_bf16 v[128:131], v[148:151], v[184:187], v[128:131]
	v_mfma_f32_16x16x32_bf16 v[120:123], v[156:159], v[184:187], v[120:123]
	v_mfma_f32_16x16x32_bf16 v[112:115], v[148:151], v[192:195], v[112:115]
	v_mfma_f32_16x16x32_bf16 v[104:107], v[156:159], v[192:195], v[104:107]
	v_mfma_f32_16x16x32_bf16 v[96:99], v[148:151], v[206:209], v[96:99]
	v_mfma_f32_16x16x32_bf16 v[88:91], v[156:159], v[206:209], v[88:91]
	v_mfma_f32_16x16x32_bf16 v[80:83], v[148:151], v[214:217], v[80:83]
	v_mfma_f32_16x16x32_bf16 v[72:75], v[156:159], v[214:217], v[72:75]
	s_setprio 0
	s_setprio 1
	v_mfma_f32_16x16x32_bf16 v[124:127], v[160:163], v[180:183], v[124:127]
	v_mfma_f32_16x16x32_bf16 v[116:119], v[172:175], v[180:183], v[116:119]
	v_mfma_f32_16x16x32_bf16 v[108:111], v[160:163], v[188:191], v[108:111]
	v_mfma_f32_16x16x32_bf16 v[100:103], v[172:175], v[188:191], v[100:103]
	v_mfma_f32_16x16x32_bf16 v[92:95], v[160:163], v[202:205], v[92:95]
	v_mfma_f32_16x16x32_bf16 v[84:87], v[172:175], v[202:205], v[84:87]
	v_mfma_f32_16x16x32_bf16 v[76:79], v[160:163], v[210:213], v[76:79]
	v_mfma_f32_16x16x32_bf16 v[68:71], v[172:175], v[210:213], v[68:71]
	v_mfma_f32_16x16x32_bf16 v[124:127], v[168:171], v[184:187], v[124:127]
	v_mfma_f32_16x16x32_bf16 v[116:119], v[176:179], v[184:187], v[116:119]
	v_mfma_f32_16x16x32_bf16 v[108:111], v[168:171], v[192:195], v[108:111]
	v_mfma_f32_16x16x32_bf16 v[100:103], v[176:179], v[192:195], v[100:103]
	v_mfma_f32_16x16x32_bf16 v[92:95], v[168:171], v[206:209], v[92:95]
	v_mfma_f32_16x16x32_bf16 v[84:87], v[176:179], v[206:209], v[84:87]
	v_mfma_f32_16x16x32_bf16 v[76:79], v[168:171], v[214:217], v[76:79]
	v_mfma_f32_16x16x32_bf16 v[68:71], v[176:179], v[214:217], v[68:71]
	s_setprio 0
	s_barrier
	s_add_u32 s24, s8, 0xfffc0080
	s_addc_u32 s25, s9, -1
	s_cmp_eq_u32 s46, 12
	s_cselect_b32 s27, s7, s25
	s_cselect_b32 s26, s17, s24
	s_cselect_b32 s25, s19, s45
	s_cselect_b32 s24, s43, s44
	v_lshl_add_u64 v[198:199], s[24:25], 0, v[134:135]
	s_add_i32 m0, s35, 0x10000
	ds_read_b128 v[180:183], v166 offset:16384
	ds_read_b128 v[184:187], v166 offset:17408
	ds_read_b128 v[188:191], v166 offset:18432
	ds_read_b128 v[192:195], v166 offset:19456
	ds_read_b128 v[202:205], v166 offset:20480
	ds_read_b128 v[206:209], v166 offset:21504
	ds_read_b128 v[210:213], v166 offset:22528
	ds_read_b128 v[214:217], v166 offset:23552
	global_load_lds_dwordx4 v[198:199], off
	s_add_i32 m0, s35, 0x12000
	s_add_u32 s48, s24, 0x40000
	v_lshl_add_u64 v[218:219], s[24:25], 0, v[0:1]
	s_addc_u32 s49, s25, 0
	global_load_lds_dwordx4 v[218:219], off
	v_lshl_add_u64 v[220:221], s[48:49], 0, v[134:135]
	s_add_i32 m0, s35, 0x14000
	v_lshl_add_u64 v[222:223], s[26:27], 0, v[132:133]
	global_load_lds_dwordx4 v[220:221], off
	s_add_i32 m0, s35, 0x16000
	v_lshl_add_u64 v[220:221], s[48:49], 0, v[0:1]
	global_load_lds_dwordx4 v[220:221], off
	v_lshl_add_u64 v[220:221], s[26:27], 0, v[136:137]
	s_waitcnt vmcnt(6) lgkmcnt(0)
	s_barrier
	s_setprio 1
	v_mfma_f32_16x16x32_bf16 v[64:67], v[144:147], v[180:183], v[64:67]
	v_mfma_f32_16x16x32_bf16 v[56:59], v[152:155], v[180:183], v[56:59]
	v_mfma_f32_16x16x32_bf16 v[48:51], v[144:147], v[188:191], v[48:51]
	v_mfma_f32_16x16x32_bf16 v[40:43], v[152:155], v[188:191], v[40:43]
	v_mfma_f32_16x16x32_bf16 v[32:35], v[144:147], v[202:205], v[32:35]
	v_mfma_f32_16x16x32_bf16 v[24:27], v[152:155], v[202:205], v[24:27]
	v_mfma_f32_16x16x32_bf16 v[16:19], v[144:147], v[210:213], v[16:19]
	v_mfma_f32_16x16x32_bf16 v[8:11], v[152:155], v[210:213], v[8:11]
	v_mfma_f32_16x16x32_bf16 v[64:67], v[148:151], v[184:187], v[64:67]
	v_mfma_f32_16x16x32_bf16 v[56:59], v[156:159], v[184:187], v[56:59]
	v_mfma_f32_16x16x32_bf16 v[48:51], v[148:151], v[192:195], v[48:51]
	v_mfma_f32_16x16x32_bf16 v[40:43], v[156:159], v[192:195], v[40:43]
	v_mfma_f32_16x16x32_bf16 v[32:35], v[148:151], v[206:209], v[32:35]
	v_mfma_f32_16x16x32_bf16 v[24:27], v[156:159], v[206:209], v[24:27]
	v_mfma_f32_16x16x32_bf16 v[16:19], v[148:151], v[214:217], v[16:19]
	v_mfma_f32_16x16x32_bf16 v[8:11], v[156:159], v[214:217], v[8:11]
	s_setprio 0
	s_setprio 1
	v_mfma_f32_16x16x32_bf16 v[60:63], v[160:163], v[180:183], v[60:63]
	v_mfma_f32_16x16x32_bf16 v[52:55], v[172:175], v[180:183], v[52:55]
	v_mfma_f32_16x16x32_bf16 v[44:47], v[160:163], v[188:191], v[44:47]
	v_mfma_f32_16x16x32_bf16 v[36:39], v[172:175], v[188:191], v[36:39]
	v_mfma_f32_16x16x32_bf16 v[28:31], v[160:163], v[202:205], v[28:31]
	v_mfma_f32_16x16x32_bf16 v[20:23], v[172:175], v[202:205], v[20:23]
	v_mfma_f32_16x16x32_bf16 v[12:15], v[160:163], v[210:213], v[12:15]
	v_mfma_f32_16x16x32_bf16 v[4:7], v[172:175], v[210:213], v[4:7]
	v_mfma_f32_16x16x32_bf16 v[60:63], v[168:171], v[184:187], v[60:63]
	v_mfma_f32_16x16x32_bf16 v[52:55], v[176:179], v[184:187], v[52:55]
	v_mfma_f32_16x16x32_bf16 v[44:47], v[168:171], v[192:195], v[44:47]
	v_mfma_f32_16x16x32_bf16 v[36:39], v[176:179], v[192:195], v[36:39]
	v_mfma_f32_16x16x32_bf16 v[28:31], v[168:171], v[206:209], v[28:31]
	v_mfma_f32_16x16x32_bf16 v[20:23], v[176:179], v[206:209], v[20:23]
	v_mfma_f32_16x16x32_bf16 v[12:15], v[168:171], v[214:217], v[12:15]
	v_mfma_f32_16x16x32_bf16 v[4:7], v[176:179], v[214:217], v[4:7]
	s_setprio 0
	s_barrier

; #define PG8_STAGE(bufoff, gbase, voff) do { _Pragma("unroll") for (int _i = 0; _i < 2; ++_i) \
;         __builtin_amdgcn_global_load_lds((const unsigned*)((const char*)(gbase) + (voff)[_i]), (PG8_LAS unsigned*)(lds + (bufoff) + ldsw + _i * 8192), 16, 0, 0); } while (0)
; #define PG8_LDA(dst, b, h) do { _Pragma("unroll") for (int m = 0; m < 4; ++m) _Pragma("unroll") for (int k = 0; k < 2; ++k) dst[m][k] = *(const PG8_LAS bf16x8*)(lds + PG8_SA(b, h) + aoff + m * 2048 + k * 1024); } while (0)
; #define PG8_LDB(dst, b, h) do { _Pragma("unroll") for (int n = 0; n < 2; ++n) _Pragma("unroll") for (int k = 0; k < 2; ++k) dst[n][k] = *(const PG8_LAS bf16x8*)(lds + PG8_SB(b, h) + boff + n * 2048 + k * 1024); } while (0)
; #define PG8_MMA(ai, bj, At, Bt) do { __builtin_amdgcn_s_setprio(1); _Pragma("unroll") for (int m = 0; m < 4; ++m) _Pragma("unroll") for (int n = 0; n < 2; ++n) _Pragma("unroll") for (int k = 0; k < 2; ++k) \
;         acc[ai][bj][m][n] = __builtin_amdgcn_mfma_f32_16x16x32_bf16(Bt[n][k], At[m][k], acc[ai][bj][m][n], 0, 0, 0); __builtin_amdgcn_s_setprio(0); } while (0)
; #define PG8_WAIT_V(n) asm volatile("s_waitcnt vmcnt(" #n ")" ::: "memory")
; #define PG8_WAIT_L(n) asm volatile("s_waitcnt lgkmcnt(" #n ")" ::: "memory")
; template <class Epi, class Sched, bool ALIGN_EPI = false, bool SP2 = false>
; __device__ __forceinline__ void gemm_phase(PG8_LAS unsigned char* lds, const Gemm g, const Sched& S, const Epi& E) {
;     ...
;             const bool last = (t == nt - 2);
;             const char* a1 = cA + (size_t)(t + 1) * kstep;
;             const char* a2 = last ? nA : cA + (size_t)(t + 2) * kstep; const char* b2 = last ? nB : cB + (size_t)(t + 2) * kstep;
;             const char* a3 = a2 + kstep; const char* b3 = b2 + kstep;
;             if (last && has_next) S.a_ready(nxt);
;             if constexpr (SP2) {
;             PG8_LDB(B0, 0, 0); PG8_LDB(B1, 0, 1); PG8_SCHED; PG8_LDA(At, 0, 0); PG8_STAGE(PG8_SA(1, 1), a1 + hstep, voffA);
;             PG8_WAIT_V(8); PG8_WAIT_L(0); PG8_BAR; PG8_MMA(0, 0, At, B0); PG8_MMA(0, 1, At, B1); PG8_BAR; PG8_SCHED;
;             PG8_LDA(At, 0, 1); PG8_STAGE(PG8_SB(0, 0), b2, voffB); PG8_STAGE(PG8_SB(0, 1), b2 + hstep, voffB); PG8_STAGE(PG8_SA(0, 0), a2, voffA);
;             PG8_WAIT_V(8); PG8_WAIT_L(0); PG8_BAR; PG8_MMA(1, 0, At, B0); PG8_MMA(1, 1, At, B1); PG8_BAR; PG8_SCHED;
.LBB0_479:
	s_add_u32 s44, s28, 0x100
	s_addc_u32 s45, s29, 0
	s_mov_b32 s53, -2
	ds_read_b128 v[68:71], v234
	ds_read_b128 v[80:83], v234 offset:1024
	ds_read_b128 v[92:95], v234 offset:2048
	ds_read_b128 v[100:103], v234 offset:3072
	ds_read_b128 v[112:115], v234 offset:16384
	ds_read_b128 v[120:123], v234 offset:17408
	ds_read_b128 v[132:135], v234 offset:18432
	ds_read_b128 v[144:147], v234 offset:19456
	v_lshl_add_u64 v[198:199], s[26:27], 0, v[204:205]
	s_add_i32 m0, s40, 0xc000
	ds_read_b128 v[156:159], v236
	ds_read_b128 v[168:171], v236 offset:1024
	ds_read_b128 v[172:175], v236 offset:2048
	ds_read_b128 v[176:179], v236 offset:3072
	ds_read_b128 v[180:183], v236 offset:4096
	ds_read_b128 v[184:187], v236 offset:5120
	ds_read_b128 v[188:191], v236 offset:6144
	ds_read_b128 v[208:211], v236 offset:7168
	global_load_lds_dwordx4 v[198:199], off
	s_add_i32 m0, s40, 0xe000
	v_lshl_add_u64 v[198:199], s[26:27], 0, v[206:207]
	global_load_lds_dwordx4 v[198:199], off
	s_waitcnt vmcnt(8) lgkmcnt(0)
	s_barrier
	s_setprio 1
	v_mfma_f32_16x16x32_bf16 v[164:167], v[68:71], v[156:159], 0
	v_mfma_f32_16x16x32_bf16 v[160:163], v[92:95], v[156:159], 0
	v_mfma_f32_16x16x32_bf16 v[140:143], v[68:71], v[172:175], 0
	v_mfma_f32_16x16x32_bf16 v[136:139], v[92:95], v[172:175], 0
	v_mfma_f32_16x16x32_bf16 v[116:119], v[68:71], v[180:183], 0
	v_mfma_f32_16x16x32_bf16 v[108:111], v[92:95], v[180:183], 0
	v_mfma_f32_16x16x32_bf16 v[88:91], v[68:71], v[188:191], 0
	v_mfma_f32_16x16x32_bf16 v[84:87], v[92:95], v[188:191], 0
	v_mfma_f32_16x16x32_bf16 v[164:167], v[80:83], v[168:171], v[164:167]
	v_mfma_f32_16x16x32_bf16 v[160:163], v[100:103], v[168:171], v[160:163]
	v_mfma_f32_16x16x32_bf16 v[140:143], v[80:83], v[176:179], v[140:143]
	v_mfma_f32_16x16x32_bf16 v[136:139], v[100:103], v[176:179], v[136:139]
	v_mfma_f32_16x16x32_bf16 v[116:119], v[80:83], v[184:187], v[116:119]
	v_mfma_f32_16x16x32_bf16 v[108:111], v[100:103], v[184:187], v[108:111]
	v_mfma_f32_16x16x32_bf16 v[88:91], v[80:83], v[208:211], v[88:91]
	v_mfma_f32_16x16x32_bf16 v[84:87], v[100:103], v[208:211], v[84:87]
	s_setprio 0
	s_setprio 1
	v_mfma_f32_16x16x32_bf16 v[152:155], v[112:115], v[156:159], 0
	v_mfma_f32_16x16x32_bf16 v[148:151], v[132:135], v[156:159], 0
	v_mfma_f32_16x16x32_bf16 v[128:131], v[112:115], v[172:175], 0
	v_mfma_f32_16x16x32_bf16 v[124:127], v[132:135], v[172:175], 0
	v_mfma_f32_16x16x32_bf16 v[104:107], v[112:115], v[180:183], 0
	v_mfma_f32_16x16x32_bf16 v[96:99], v[132:135], v[180:183], 0
	v_mfma_f32_16x16x32_bf16 v[76:79], v[112:115], v[188:191], 0
	v_mfma_f32_16x16x32_bf16 v[72:75], v[132:135], v[188:191], 0
	v_mfma_f32_16x16x32_bf16 v[152:155], v[120:123], v[168:171], v[152:155]
	v_mfma_f32_16x16x32_bf16 v[148:151], v[144:147], v[168:171], v[148:151]
	v_mfma_f32_16x16x32_bf16 v[128:131], v[120:123], v[176:179], v[128:131]
	v_mfma_f32_16x16x32_bf16 v[124:127], v[144:147], v[176:179], v[124:127]
	v_mfma_f32_16x16x32_bf16 v[104:107], v[120:123], v[184:187], v[104:107]
	v_mfma_f32_16x16x32_bf16 v[96:99], v[144:147], v[184:187], v[96:99]
	v_mfma_f32_16x16x32_bf16 v[76:79], v[120:123], v[208:211], v[76:79]
	v_mfma_f32_16x16x32_bf16 v[72:75], v[144:147], v[208:211], v[72:75]
	s_setprio 0
	s_barrier
	s_add_u32 s8, s26, 0x100
	s_addc_u32 s9, s27, 0
	s_cmp_eq_u32 s53, 40
	s_cselect_b32 s31, s23, s9
	s_cselect_b32 s30, s22, s8
	s_cselect_b32 s29, s25, s45
	s_cselect_b32 s28, s24, s44
	v_lshl_add_u64 v[198:199], s[28:29], 0, v[192:193]
	s_add_i32 m0, s39, 0x10000
	ds_read_b128 v[156:159], v236 offset:16384
	ds_read_b128 v[168:171], v236 offset:17408
	ds_read_b128 v[172:175], v236 offset:18432
	ds_read_b128 v[176:179], v236 offset:19456
	ds_read_b128 v[180:183], v236 offset:20480
	ds_read_b128 v[184:187], v236 offset:21504
	ds_read_b128 v[188:191], v236 offset:22528
	ds_read_b128 v[208:211], v236 offset:23552
	global_load_lds_dwordx4 v[198:199], off
	s_add_i32 m0, s39, 0x12000
	s_add_u32 s26, s28, 0xb0000
	v_lshl_add_u64 v[212:213], s[28:29], 0, v[202:203]
	s_addc_u32 s27, s29, 0
	global_load_lds_dwordx4 v[212:213], off
	v_lshl_add_u64 v[214:215], s[26:27], 0, v[192:193]
	s_add_i32 m0, s39, 0x14000
	v_lshl_add_u64 v[216:217], s[30:31], 0, v[194:195]
	global_load_lds_dwordx4 v[214:215], off
	s_add_i32 m0, s39, 0x16000
	v_lshl_add_u64 v[214:215], s[26:27], 0, v[202:203]
	global_load_lds_dwordx4 v[214:215], off
	v_lshl_add_u64 v[214:215], s[30:31], 0, v[0:1]
	s_waitcnt vmcnt(6) lgkmcnt(0)
	s_barrier
	s_setprio 1
	v_mfma_f32_16x16x32_bf16 v[64:67], v[68:71], v[156:159], 0
	v_mfma_f32_16x16x32_bf16 v[60:63], v[92:95], v[156:159], 0
	v_mfma_f32_16x16x32_bf16 v[48:51], v[68:71], v[172:175], 0
	v_mfma_f32_16x16x32_bf16 v[44:47], v[92:95], v[172:175], 0
	v_mfma_f32_16x16x32_bf16 v[32:35], v[68:71], v[180:183], 0
	v_mfma_f32_16x16x32_bf16 v[28:31], v[92:95], v[180:183], 0
	v_mfma_f32_16x16x32_bf16 v[16:19], v[68:71], v[188:191], 0
	v_mfma_f32_16x16x32_bf16 v[12:15], v[92:95], v[188:191], 0
	v_mfma_f32_16x16x32_bf16 v[64:67], v[80:83], v[168:171], v[64:67]
	v_mfma_f32_16x16x32_bf16 v[60:63], v[100:103], v[168:171], v[60:63]
	v_mfma_f32_16x16x32_bf16 v[48:51], v[80:83], v[176:179], v[48:51]
	v_mfma_f32_16x16x32_bf16 v[44:47], v[100:103], v[176:179], v[44:47]
	v_mfma_f32_16x16x32_bf16 v[32:35], v[80:83], v[184:187], v[32:35]
	v_mfma_f32_16x16x32_bf16 v[28:31], v[100:103], v[184:187], v[28:31]
	v_mfma_f32_16x16x32_bf16 v[16:19], v[80:83], v[208:211], v[16:19]
	v_mfma_f32_16x16x32_bf16 v[12:15], v[100:103], v[208:211], v[12:15]
	s_setprio 0
	s_setprio 1
	v_mfma_f32_16x16x32_bf16 v[56:59], v[112:115], v[156:159], 0
	v_mfma_f32_16x16x32_bf16 v[52:55], v[132:135], v[156:159], 0
	v_mfma_f32_16x16x32_bf16 v[40:43], v[112:115], v[172:175], 0
	v_mfma_f32_16x16x32_bf16 v[36:39], v[132:135], v[172:175], 0
	v_mfma_f32_16x16x32_bf16 v[24:27], v[112:115], v[180:183], 0
	v_mfma_f32_16x16x32_bf16 v[20:23], v[132:135], v[180:183], 0
	v_mfma_f32_16x16x32_bf16 v[8:11], v[112:115], v[188:191], 0
	v_mfma_f32_16x16x32_bf16 v[4:7], v[132:135], v[188:191], 0
	v_mfma_f32_16x16x32_bf16 v[56:59], v[120:123], v[168:171], v[56:59]
	v_mfma_f32_16x16x32_bf16 v[52:55], v[144:147], v[168:171], v[52:55]
	v_mfma_f32_16x16x32_bf16 v[40:43], v[120:123], v[176:179], v[40:43]
	v_mfma_f32_16x16x32_bf16 v[36:39], v[144:147], v[176:179], v[36:39]
	v_mfma_f32_16x16x32_bf16 v[24:27], v[120:123], v[184:187], v[24:27]
	v_mfma_f32_16x16x32_bf16 v[20:23], v[144:147], v[184:187], v[20:23]
	v_mfma_f32_16x16x32_bf16 v[8:11], v[120:123], v[208:211], v[8:11]
	v_mfma_f32_16x16x32_bf16 v[4:7], v[144:147], v[208:211], v[4:7]
	s_setprio 0
	s_barrier
	s_branch .Lkmid_3
; #define PG8_STAGE(bufoff, gbase, voff) do { _Pragma("unroll") for (int _i = 0; _i < 2; ++_i) \
;         __builtin_amdgcn_global_load_lds((const unsigned*)((const char*)(gbase) + (voff)[_i]), (PG8_LAS unsigned*)(lds + (bufoff) + ldsw + _i * 8192), 16, 0, 0); } while (0)
; #define PG8_LDA(dst, b, h) do { _Pragma("unroll") for (int m = 0; m < 4; ++m) _Pragma("unroll") for (int k = 0; k < 2; ++k) dst[m][k] = *(const PG8_LAS bf16x8*)(lds + PG8_SA(b, h) + aoff + m * 2048 + k * 1024); } while (0)
; #define PG8_LDB(dst, b, h) do { _Pragma("unroll") for (int n = 0; n < 2; ++n) _Pragma("unroll") for (int k = 0; k < 2; ++k) dst[n][k] = *(const PG8_LAS bf16x8*)(lds + PG8_SB(b, h) + boff + n * 2048 + k * 1024); } while (0)
; #define PG8_MMA(ai, bj, At, Bt) do { __builtin_amdgcn_s_setprio(1); _Pragma("unroll") for (int m = 0; m < 4; ++m) _Pragma("unroll") for (int n = 0; n < 2; ++n) _Pragma("unroll") for (int k = 0; k < 2; ++k) \
;         acc[ai][bj][m][n] = __builtin_amdgcn_mfma_f32_16x16x32_bf16(Bt[n][k], At[m][k], acc[ai][bj][m][n], 0, 0, 0); __builtin_amdgcn_s_setprio(0); } while (0)
; #define PG8_WAIT_V(n) asm volatile("s_waitcnt vmcnt(" #n ")" ::: "memory")
; #define PG8_WAIT_L(n) asm volatile("s_waitcnt lgkmcnt(" #n ")" ::: "memory")
; template <class Epi, class Sched, bool ALIGN_EPI = false, bool SP2 = false>
; __device__ __forceinline__ void gemm_phase(PG8_LAS unsigned char* lds, const Gemm g, const Sched& S, const Epi& E) {
;     ...
;             const bool last = (t == nt - 2);
;             const char* a1 = cA + (size_t)(t + 1) * kstep;
;             const char* a2 = last ? nA : cA + (size_t)(t + 2) * kstep; const char* b2 = last ? nB : cB + (size_t)(t + 2) * kstep;
;             const char* a3 = a2 + kstep; const char* b3 = b2 + kstep;
;             if (last && has_next) S.a_ready(nxt);
;             if constexpr (SP2) {
;             PG8_LDB(B0, 0, 0); PG8_LDB(B1, 0, 1); PG8_SCHED; PG8_LDA(At, 0, 0); PG8_STAGE(PG8_SA(1, 1), a1 + hstep, voffA);
;             PG8_WAIT_V(8); PG8_WAIT_L(0); PG8_BAR; PG8_MMA(0, 0, At, B0); PG8_MMA(0, 1, At, B1); PG8_BAR; PG8_SCHED;
;             PG8_LDA(At, 0, 1); PG8_STAGE(PG8_SB(0, 0), b2, voffB); PG8_STAGE(PG8_SB(0, 1), b2 + hstep, voffB); PG8_STAGE(PG8_SA(0, 0), a2, voffA);
;             PG8_WAIT_V(8); PG8_WAIT_L(0); PG8_BAR; PG8_MMA(1, 0, At, B0); PG8_MMA(1, 1, At, B1); PG8_BAR; PG8_SCHED;
.LBB0_480:
	s_add_i32 m0, s47, 0xffffff80
	ds_read_b128 v[68:71], v234
	ds_read_b128 v[80:83], v234 offset:1024
	ds_read_b128 v[92:95], v234 offset:2048
	ds_read_b128 v[100:103], v234 offset:3072
	ds_read_b128 v[112:115], v234 offset:16384
	ds_read_b128 v[120:123], v234 offset:17408
	ds_read_b128 v[132:135], v234 offset:18432
	ds_read_b128 v[144:147], v234 offset:19456
	global_load_lds_dwordx4 v[214:215], off offset:128
	s_add_i32 m0, s48, 0xffffff80
	v_lshl_add_u64 v[198:199], s[26:27], 0, v[204:205]
	global_load_lds_dwordx4 v[216:217], off offset:128
	s_add_i32 m0, s40, 0xc000
	ds_read_b128 v[156:159], v236
	ds_read_b128 v[168:171], v236 offset:1024
	ds_read_b128 v[172:175], v236 offset:2048
	ds_read_b128 v[176:179], v236 offset:3072
	ds_read_b128 v[180:183], v236 offset:4096
	ds_read_b128 v[184:187], v236 offset:5120
	ds_read_b128 v[188:191], v236 offset:6144
	ds_read_b128 v[208:211], v236 offset:7168
	global_load_lds_dwordx4 v[198:199], off
	s_add_i32 m0, s40, 0xe000
	v_lshl_add_u64 v[198:199], s[26:27], 0, v[206:207]
	global_load_lds_dwordx4 v[198:199], off
	s_waitcnt vmcnt(8) lgkmcnt(0)
	s_barrier
	s_setprio 1
	v_mfma_f32_16x16x32_bf16 v[164:167], v[68:71], v[156:159], v[164:167]
	v_mfma_f32_16x16x32_bf16 v[160:163], v[92:95], v[156:159], v[160:163]
	v_mfma_f32_16x16x32_bf16 v[140:143], v[68:71], v[172:175], v[140:143]
	v_mfma_f32_16x16x32_bf16 v[136:139], v[92:95], v[172:175], v[136:139]
	v_mfma_f32_16x16x32_bf16 v[116:119], v[68:71], v[180:183], v[116:119]
	v_mfma_f32_16x16x32_bf16 v[108:111], v[92:95], v[180:183], v[108:111]
	v_mfma_f32_16x16x32_bf16 v[88:91], v[68:71], v[188:191], v[88:91]
	v_mfma_f32_16x16x32_bf16 v[84:87], v[92:95], v[188:191], v[84:87]
	v_mfma_f32_16x16x32_bf16 v[164:167], v[80:83], v[168:171], v[164:167]
	v_mfma_f32_16x16x32_bf16 v[160:163], v[100:103], v[168:171], v[160:163]
	v_mfma_f32_16x16x32_bf16 v[140:143], v[80:83], v[176:179], v[140:143]
	v_mfma_f32_16x16x32_bf16 v[136:139], v[100:103], v[176:179], v[136:139]
	v_mfma_f32_16x16x32_bf16 v[116:119], v[80:83], v[184:187], v[116:119]
	v_mfma_f32_16x16x32_bf16 v[108:111], v[100:103], v[184:187], v[108:111]
	v_mfma_f32_16x16x32_bf16 v[88:91], v[80:83], v[208:211], v[88:91]
	v_mfma_f32_16x16x32_bf16 v[84:87], v[100:103], v[208:211], v[84:87]
	s_setprio 0
	s_setprio 1
	v_mfma_f32_16x16x32_bf16 v[152:155], v[112:115], v[156:159], v[152:155]
	v_mfma_f32_16x16x32_bf16 v[148:151], v[132:135], v[156:159], v[148:151]
	v_mfma_f32_16x16x32_bf16 v[128:131], v[112:115], v[172:175], v[128:131]
	v_mfma_f32_16x16x32_bf16 v[124:127], v[132:135], v[172:175], v[124:127]
	v_mfma_f32_16x16x32_bf16 v[104:107], v[112:115], v[180:183], v[104:107]
	v_mfma_f32_16x16x32_bf16 v[96:99], v[132:135], v[180:183], v[96:99]
	v_mfma_f32_16x16x32_bf16 v[76:79], v[112:115], v[188:191], v[76:79]
	v_mfma_f32_16x16x32_bf16 v[72:75], v[132:135], v[188:191], v[72:75]
	v_mfma_f32_16x16x32_bf16 v[152:155], v[120:123], v[168:171], v[152:155]
	v_mfma_f32_16x16x32_bf16 v[148:151], v[144:147], v[168:171], v[148:151]
	v_mfma_f32_16x16x32_bf16 v[128:131], v[120:123], v[176:179], v[128:131]
	v_mfma_f32_16x16x32_bf16 v[124:127], v[144:147], v[176:179], v[124:127]
	v_mfma_f32_16x16x32_bf16 v[104:107], v[120:123], v[184:187], v[104:107]
	v_mfma_f32_16x16x32_bf16 v[96:99], v[144:147], v[184:187], v[96:99]
	v_mfma_f32_16x16x32_bf16 v[76:79], v[120:123], v[208:211], v[76:79]
	v_mfma_f32_16x16x32_bf16 v[72:75], v[144:147], v[208:211], v[72:75]
	s_setprio 0
	s_barrier
	s_add_u32 s8, s26, 0x100
	s_addc_u32 s9, s27, 0
	s_cmp_eq_u32 s53, 40
	s_cselect_b32 s31, s23, s9
	s_cselect_b32 s30, s22, s8
	s_cselect_b32 s29, s25, s45
	s_cselect_b32 s28, s24, s44
	v_lshl_add_u64 v[198:199], s[28:29], 0, v[192:193]
	s_add_i32 m0, s39, 0x10000
	ds_read_b128 v[156:159], v236 offset:16384
	ds_read_b128 v[168:171], v236 offset:17408
	ds_read_b128 v[172:175], v236 offset:18432
	ds_read_b128 v[176:179], v236 offset:19456
	ds_read_b128 v[180:183], v236 offset:20480
	ds_read_b128 v[184:187], v236 offset:21504
	ds_read_b128 v[188:191], v236 offset:22528
	ds_read_b128 v[208:211], v236 offset:23552
	global_load_lds_dwordx4 v[198:199], off
	s_add_i32 m0, s39, 0x12000
	s_add_u32 s26, s28, 0xb0000
	v_lshl_add_u64 v[212:213], s[28:29], 0, v[202:203]
	s_addc_u32 s27, s29, 0
	global_load_lds_dwordx4 v[212:213], off
	v_lshl_add_u64 v[214:215], s[26:27], 0, v[192:193]
	s_add_i32 m0, s39, 0x14000
	v_lshl_add_u64 v[216:217], s[30:31], 0, v[194:195]
	global_load_lds_dwordx4 v[214:215], off
	s_add_i32 m0, s39, 0x16000
	v_lshl_add_u64 v[214:215], s[26:27], 0, v[202:203]
	global_load_lds_dwordx4 v[214:215], off
	v_lshl_add_u64 v[214:215], s[30:31], 0, v[0:1]
	s_waitcnt vmcnt(6) lgkmcnt(0)
	s_barrier
	s_setprio 1
	v_mfma_f32_16x16x32_bf16 v[64:67], v[68:71], v[156:159], v[64:67]
	v_mfma_f32_16x16x32_bf16 v[60:63], v[92:95], v[156:159], v[60:63]
	v_mfma_f32_16x16x32_bf16 v[48:51], v[68:71], v[172:175], v[48:51]
	v_mfma_f32_16x16x32_bf16 v[44:47], v[92:95], v[172:175], v[44:47]
	v_mfma_f32_16x16x32_bf16 v[32:35], v[68:71], v[180:183], v[32:35]
	v_mfma_f32_16x16x32_bf16 v[28:31], v[92:95], v[180:183], v[28:31]
	v_mfma_f32_16x16x32_bf16 v[16:19], v[68:71], v[188:191], v[16:19]
	v_mfma_f32_16x16x32_bf16 v[12:15], v[92:95], v[188:191], v[12:15]
	v_mfma_f32_16x16x32_bf16 v[64:67], v[80:83], v[168:171], v[64:67]
	v_mfma_f32_16x16x32_bf16 v[60:63], v[100:103], v[168:171], v[60:63]
	v_mfma_f32_16x16x32_bf16 v[48:51], v[80:83], v[176:179], v[48:51]
	v_mfma_f32_16x16x32_bf16 v[44:47], v[100:103], v[176:179], v[44:47]
	v_mfma_f32_16x16x32_bf16 v[32:35], v[80:83], v[184:187], v[32:35]
	v_mfma_f32_16x16x32_bf16 v[28:31], v[100:103], v[184:187], v[28:31]
	v_mfma_f32_16x16x32_bf16 v[16:19], v[80:83], v[208:211], v[16:19]
	v_mfma_f32_16x16x32_bf16 v[12:15], v[100:103], v[208:211], v[12:15]
	s_setprio 0
	s_setprio 1
	v_mfma_f32_16x16x32_bf16 v[56:59], v[112:115], v[156:159], v[56:59]
	v_mfma_f32_16x16x32_bf16 v[52:55], v[132:135], v[156:159], v[52:55]
	v_mfma_f32_16x16x32_bf16 v[40:43], v[112:115], v[172:175], v[40:43]
	v_mfma_f32_16x16x32_bf16 v[36:39], v[132:135], v[172:175], v[36:39]
	v_mfma_f32_16x16x32_bf16 v[24:27], v[112:115], v[180:183], v[24:27]
	v_mfma_f32_16x16x32_bf16 v[20:23], v[132:135], v[180:183], v[20:23]
	v_mfma_f32_16x16x32_bf16 v[8:11], v[112:115], v[188:191], v[8:11]
	v_mfma_f32_16x16x32_bf16 v[4:7], v[132:135], v[188:191], v[4:7]
	v_mfma_f32_16x16x32_bf16 v[56:59], v[120:123], v[168:171], v[56:59]
	v_mfma_f32_16x16x32_bf16 v[52:55], v[144:147], v[168:171], v[52:55]
	v_mfma_f32_16x16x32_bf16 v[40:43], v[120:123], v[176:179], v[40:43]
	v_mfma_f32_16x16x32_bf16 v[36:39], v[144:147], v[176:179], v[36:39]
	v_mfma_f32_16x16x32_bf16 v[24:27], v[120:123], v[184:187], v[24:27]
	v_mfma_f32_16x16x32_bf16 v[20:23], v[144:147], v[184:187], v[20:23]
	v_mfma_f32_16x16x32_bf16 v[8:11], v[120:123], v[208:211], v[8:11]
	v_mfma_f32_16x16x32_bf16 v[4:7], v[144:147], v[208:211], v[4:7]
	s_setprio 0
	s_barrier
